# v3 + scan chunk-top vmcnt(1) + P16 route_b tail: 64 dynamically indexed words staged through conflict-free per-thread LDS column instead of dependent scattered global loads
# speedup vs baseline: 1.0237x; 1.0237x over previous
.LBB0_483:
	s_or_b64 exec, exec, s[0:1]
	v_readlane_b32 s36, v248, 32
	v_readlane_b32 s37, v248, 33
	v_readlane_b32 s38, v248, 34
	v_readlane_b32 s39, v248, 35
	v_lshl_add_u64 v[92:93], s[36:37], 0, v[40:41]
	s_mov_b32 s28, 0
	v_lshl_add_u64 v[90:91], s[38:39], 0, v[40:41]
	v_mov_b64_e32 v[102:103], v[100:101]
	v_mov_b64_e32 v[104:105], v[100:101]
	v_mov_b64_e32 v[106:107], v[100:101]
	v_mov_b64_e32 v[108:109], v[100:101]
	v_mov_b64_e32 v[110:111], v[100:101]
	v_mov_b64_e32 v[112:113], v[100:101]
	v_mov_b64_e32 v[114:115], v[100:101]
	v_readlane_b32 s40, v248, 36
	v_readlane_b32 s41, v248, 37
	v_readlane_b32 s42, v248, 38
	v_readlane_b32 s43, v248, 39
	s_waitcnt vmcnt(0)
	s_branch .LBB0_485

.LBB0_485:
	ds_read_b128 v[8:11], v84 offset:30784
	s_waitcnt vmcnt(4)
	v_lshlrev_b32_e32 v16, 16, v88
	v_and_b32_e32 v17, 0xffff0000, v88
	s_waitcnt vmcnt(2)
	v_lshlrev_b32_e32 v12, 16, v94
	v_and_b32_e32 v13, 0xffff0000, v94
	v_pk_add_f32 v[18:19], v[12:13], v[16:17] neg_lo:[0,1] neg_hi:[0,1]
	ds_read_b128 v[12:15], v84 offset:31296
	s_waitcnt lgkmcnt(1)
	v_pk_fma_f32 v[8:9], v[18:19], v[8:9], v[16:17]
	v_lshlrev_b32_e32 v16, 16, v89
	v_and_b32_e32 v17, 0xffff0000, v89
	v_lshlrev_b32_e32 v18, 16, v95
	v_and_b32_e32 v19, 0xffff0000, v95
	v_pk_add_f32 v[18:19], v[18:19], v[16:17] neg_lo:[0,1] neg_hi:[0,1]
	v_lshlrev_b32_e32 v222, 16, v76
	v_pk_fma_f32 v[10:11], v[18:19], v[10:11], v[16:17]
	v_lshlrev_b32_e32 v16, 16, v86
	v_and_b32_e32 v17, 0xffff0000, v86
	s_waitcnt vmcnt(1)
	v_lshlrev_b32_e32 v18, 16, v98
	v_and_b32_e32 v19, 0xffff0000, v98
	v_pk_add_f32 v[18:19], v[18:19], v[16:17] neg_lo:[0,1] neg_hi:[0,1]
	ds_write_b128 v171, v[8:11] offset:16384
	s_waitcnt lgkmcnt(1)
	v_pk_fma_f32 v[12:13], v[18:19], v[12:13], v[16:17]
	v_lshlrev_b32_e32 v16, 16, v87
	v_and_b32_e32 v17, 0xffff0000, v87
	v_lshlrev_b32_e32 v18, 16, v99
	v_and_b32_e32 v19, 0xffff0000, v99
	v_pk_add_f32 v[18:19], v[18:19], v[16:17] neg_lo:[0,1] neg_hi:[0,1]
	v_and_b32_e32 v223, 0xffff0000, v76
	v_pk_fma_f32 v[14:15], v[18:19], v[14:15], v[16:17]
	ds_write_b128 v171, v[12:15] offset:20480
	ds_write_b128 v164, v[4:7]
	ds_read_b128 v[12:15], v84 offset:31040
	ds_write_b128 v164, v[0:3] offset:16
	s_waitcnt lgkmcnt(0)
	s_barrier
	ds_read_b128 v[16:19], v196 offset:38464
	ds_read_b128 v[20:23], v197 offset:61248
	ds_read_b128 v[116:119], v196 offset:38528
	ds_read_b128 v[210:213], v197 offset:61312
	ds_read_b128 v[214:217], v196 offset:38592
	s_waitcnt lgkmcnt(3)
	v_mfma_f32_16x16x32_bf16 v[16:19], v[16:19], v[20:23], 0
	ds_read_b128 v[20:23], v197 offset:61376
	ds_read_b128 v[218:221], v196 offset:38656
	v_lshlrev_b32_e32 v224, 16, v96
	v_and_b32_e32 v225, 0xffff0000, v96
	s_waitcnt lgkmcnt(3)
	v_mfma_f32_16x16x32_bf16 v[16:19], v[116:119], v[210:213], v[16:19]
	ds_read_b128 v[116:119], v195 offset:33856
	ds_read_b128 v[210:213], v197 offset:61440
	s_waitcnt lgkmcnt(3)
	v_mfma_f32_16x16x32_bf16 v[16:19], v[214:217], v[20:23], v[16:19]
	ds_read_b128 v[20:23], v167 offset:42816
	ds_read_b128 v[214:217], v195 offset:33920
	s_waitcnt lgkmcnt(2)
	v_mfma_f32_16x16x32_bf16 v[16:19], v[218:221], v[210:213], v[16:19]
	ds_read_b128 v[210:213], v167 offset:42880
	v_pk_add_f32 v[218:219], v[224:225], v[222:223] neg_lo:[0,1] neg_hi:[0,1]
	s_waitcnt lgkmcnt(2)
	v_mfma_f32_16x16x32_bf16 v[20:23], v[116:119], v[20:23], 0
	v_fma_f32 v12, v218, v12, v222
	v_fma_f32 v13, v219, v13, v223
	ds_read_b128 v[116:119], v195 offset:36160
	ds_read_b128 v[218:221], v167 offset:52032
	s_waitcnt lgkmcnt(2)
	v_mfma_f32_16x16x32_bf16 v[20:23], v[214:217], v[210:213], v[20:23]
	ds_read_b128 v[210:213], v195 offset:36224
	ds_read_b128 v[214:217], v167 offset:52096
	s_waitcnt lgkmcnt(2)
	v_mfma_f32_16x16x32_bf16 v[116:119], v[116:119], v[218:221], 0
	s_nop 3
	v_add_f32_e32 v20, v207, v20
	v_mul_f32_e32 v20, 0xbfb8aa3b, v20
	v_exp_f32_e32 v20, v20
	s_waitcnt lgkmcnt(0)
	v_mfma_f32_16x16x32_bf16 v[116:119], v[210:213], v[214:217], v[116:119]
	v_add_f32_e32 v21, v207, v21
	v_mul_f32_e32 v21, 0xbfb8aa3b, v21
	v_add_f32_e32 v20, 1.0, v20
	v_div_scale_f32 v40, s[0:1], v20, v20, 1.0
	v_rcp_f32_e32 v209, v40
	s_nop 2
	v_add_f32_e32 v116, v208, v116
	v_mul_f32_e32 v116, 0xbfb8aa3b, v116
	v_exp_f32_e32 v116, v116
	v_fma_f32 v210, -v40, v209, 1.0
	v_fmac_f32_e32 v209, v210, v209
	v_div_scale_f32 v210, vcc, 1.0, v20, 1.0
	v_mul_f32_e32 v211, v210, v209
	v_fma_f32 v212, -v40, v211, v210
	v_fmac_f32_e32 v211, v212, v209
	v_fma_f32 v40, -v40, v211, v210
	v_div_fmas_f32 v40, v40, v209, v211
	v_div_fixup_f32 v20, v40, v20, 1.0
	v_add_f32_e32 v40, 1.0, v116
	v_div_scale_f32 v116, s[0:1], v40, v40, 1.0
	v_rcp_f32_e32 v209, v116
	v_exp_f32_e32 v21, v21
	v_add_f32_e32 v117, v208, v117
	v_mul_f32_e32 v117, 0xbfb8aa3b, v117
	v_fma_f32 v210, -v116, v209, 1.0
	v_fmac_f32_e32 v209, v210, v209
	v_div_scale_f32 v210, vcc, 1.0, v40, 1.0
	v_mul_f32_e32 v211, v210, v209
	v_fma_f32 v212, -v116, v211, v210
	v_fmac_f32_e32 v211, v212, v209
	v_add_f32_e32 v21, 1.0, v21
	v_fma_f32 v116, -v116, v211, v210
	v_div_scale_f32 v210, s[0:1], v21, v21, 1.0
	v_rcp_f32_e32 v212, v210
	v_div_fmas_f32 v116, v116, v209, v211
	v_exp_f32_e32 v117, v117
	v_mul_f32_e32 v20, 0xbf1b4598, v20
	v_fma_f32 v209, -v210, v212, 1.0
	v_fmac_f32_e32 v212, v209, v212
	v_div_scale_f32 v209, vcc, 1.0, v21, 1.0
	v_mul_f32_e32 v211, v209, v212
	v_fma_f32 v213, -v210, v211, v209
	v_fmac_f32_e32 v211, v213, v212
	v_fma_f32 v209, -v210, v211, v209
	v_div_fmas_f32 v209, v209, v212, v211
	v_div_fixup_f32 v21, v209, v21, 1.0
	v_add_f32_e32 v117, 1.0, v117
	v_mul_f32_e32 v21, 0xbf1b4598, v21
	v_div_scale_f32 v209, s[0:1], v117, v117, 1.0
	v_mul_f32_e32 v20, 0x3fb8aa3b, v20
	v_mul_f32_e32 v21, 0x3fb8aa3b, v21
	v_rcp_f32_e32 v210, v209
	v_exp_f32_e32 v20, v20
	v_exp_f32_e32 v21, v21
	v_div_fixup_f32 v40, v116, v40, 1.0
	v_bfe_u32 v116, v16, 16, 1
	v_add3_u32 v16, v16, v116, s91
	ds_write_b16_d16_hi v199, v16 offset:28736
	ds_write2st64_b32 v198, v20, v21 offset1:1
	v_fma_f32 v16, -v209, v210, 1.0
	v_fmac_f32_e32 v210, v16, v210
	v_div_scale_f32 v16, vcc, 1.0, v117, 1.0
	v_mul_f32_e32 v20, v16, v210
	v_fma_f32 v21, -v209, v20, v16
	v_fmac_f32_e32 v20, v21, v210
	v_add_f32_e32 v21, v207, v22
	v_mul_f32_e32 v21, 0xbfb8aa3b, v21
	v_exp_f32_e32 v21, v21
	v_fma_f32 v16, -v209, v20, v16
	v_div_fmas_f32 v16, v16, v210, v20
	v_div_fixup_f32 v16, v16, v117, 1.0
	ds_write2st64_b32 v198, v40, v16 offset0:96 offset1:97
	v_add_f32_e32 v16, 1.0, v21
	v_div_scale_f32 v20, s[0:1], v16, v16, 1.0
	v_rcp_f32_e32 v21, v20
	v_bfe_u32 v22, v17, 16, 1
	v_add3_u32 v17, v17, v22, s91
	ds_write_b16_d16_hi v199, v17 offset:28864
	v_fma_f32 v17, -v20, v21, 1.0
	v_fmac_f32_e32 v21, v17, v21
	v_div_scale_f32 v17, vcc, 1.0, v16, 1.0
	v_mul_f32_e32 v22, v17, v21
	v_fma_f32 v40, -v20, v22, v17
	v_fmac_f32_e32 v22, v40, v21
	v_fma_f32 v17, -v20, v22, v17
	v_add_f32_e32 v20, v208, v118
	v_mul_f32_e32 v20, 0xbfb8aa3b, v20
	v_exp_f32_e32 v20, v20
	v_div_fmas_f32 v17, v17, v21, v22
	v_div_fixup_f32 v16, v17, v16, 1.0
	v_add_f32_e32 v23, v207, v23
	v_add_f32_e32 v17, 1.0, v20
	v_div_scale_f32 v20, s[0:1], v17, v17, 1.0
	v_rcp_f32_e32 v21, v20
	v_mul_f32_e32 v23, 0xbfb8aa3b, v23
	v_exp_f32_e32 v23, v23
	v_mul_f32_e32 v16, 0xbf1b4598, v16
	v_fma_f32 v22, -v20, v21, 1.0
	v_fmac_f32_e32 v21, v22, v21
	v_div_scale_f32 v22, vcc, 1.0, v17, 1.0
	v_mul_f32_e32 v40, v22, v21
	v_fma_f32 v116, -v20, v40, v22
	v_fmac_f32_e32 v40, v116, v21
	v_fma_f32 v20, -v20, v40, v22
	v_add_f32_e32 v22, 1.0, v23
	v_div_scale_f32 v23, s[0:1], v22, v22, 1.0
	v_rcp_f32_e32 v116, v23
	v_div_fmas_f32 v20, v20, v21, v40
	v_mul_f32_e32 v16, 0x3fb8aa3b, v16
	v_exp_f32_e32 v16, v16
	v_fma_f32 v21, -v23, v116, 1.0
	v_fmac_f32_e32 v116, v21, v116
	v_div_scale_f32 v21, vcc, 1.0, v22, 1.0
	v_mul_f32_e32 v40, v21, v116
	v_fma_f32 v117, -v23, v40, v21
	v_fmac_f32_e32 v40, v117, v116
	v_fma_f32 v21, -v23, v40, v21
	v_div_fmas_f32 v21, v21, v116, v40
	v_div_fixup_f32 v21, v21, v22, 1.0
	v_add_f32_e32 v22, v208, v119
	v_mul_f32_e32 v22, 0xbfb8aa3b, v22
	v_exp_f32_e32 v22, v22
	v_mul_f32_e32 v21, 0xbf1b4598, v21
	v_mul_f32_e32 v21, 0x3fb8aa3b, v21
	v_exp_f32_e32 v21, v21
	v_add_f32_e32 v22, 1.0, v22
	v_div_scale_f32 v23, s[0:1], v22, v22, 1.0
	v_rcp_f32_e32 v40, v23
	v_div_fixup_f32 v17, v20, v17, 1.0
	v_bfe_u32 v20, v18, 16, 1
	v_add3_u32 v18, v18, v20, s91
	ds_write_b16_d16_hi v199, v18 offset:28992
	ds_write2st64_b32 v198, v16, v21 offset0:2 offset1:3
	v_fma_f32 v16, -v23, v40, 1.0
	v_fmac_f32_e32 v40, v16, v40
	v_div_scale_f32 v16, vcc, 1.0, v22, 1.0
	v_mul_f32_e32 v18, v16, v40
	v_fma_f32 v20, -v23, v18, v16
	v_fmac_f32_e32 v18, v20, v40
	v_fma_f32 v16, -v23, v18, v16
	v_div_fmas_f32 v16, v16, v40, v18
	v_div_fixup_f32 v16, v16, v22, 1.0
	ds_write2st64_b32 v198, v17, v16 offset0:98 offset1:99
	v_bfe_u32 v16, v19, 16, 1
	v_add3_u32 v16, v19, v16, s91
	ds_write_b16_d16_hi v199, v16 offset:29120
	s_waitcnt lgkmcnt(0)
	s_barrier
	ds_read_b128 v[16:19], v205 offset:31552
	v_lshlrev_b32_e32 v218, 16, v77
	v_and_b32_e32 v219, 0xffff0000, v77
	v_lshlrev_b32_e32 v20, 16, v97
	v_and_b32_e32 v21, 0xffff0000, v97
	v_pk_add_f32 v[20:21], v[20:21], v[218:219] neg_lo:[0,1] neg_hi:[0,1]
	s_waitcnt lgkmcnt(0)
	v_pk_mul_f32 v[116:117], v[12:13], v[16:17]
	v_pk_fma_f32 v[22:23], v[20:21], v[14:15], v[218:219]
	v_pk_mul_f32 v[14:15], v[116:117], v[116:117]
	v_pk_mul_f32 v[118:119], v[22:23], v[18:19]
	v_add_f32_e32 v14, v14, v15
	v_pk_mul_f32 v[16:17], v[118:119], v[118:119]
	s_mov_b32 s0, 0xf800000
	v_add_f32_e32 v14, v14, v16
	v_add_f32_e32 v14, v14, v17
	s_nop 1
	v_add_f32_dpp v14, v14, v14 row_ror:8 row_mask:0xf bank_mask:0xf bound_ctrl:1
	s_nop 1
	v_add_f32_dpp v14, v14, v14 row_ror:4 row_mask:0xf bank_mask:0xf bound_ctrl:1
	s_nop 1
	v_add_f32_dpp v14, v14, v14 row_ror:2 row_mask:0xf bank_mask:0xf bound_ctrl:1
	s_nop 1
	v_add_f32_dpp v14, v14, v14 row_ror:1 row_mask:0xf bank_mask:0xf bound_ctrl:1
	v_mul_f32_e32 v15, 0x4f800000, v14
	v_cmp_gt_f32_e32 vcc, s0, v14
	s_nop 1
	v_cndmask_b32_e32 v14, v14, v15, vcc
	v_sqrt_f32_e32 v15, v14
	s_nop 0
	v_add_u32_e32 v16, -1, v15
	v_fma_f32 v17, -v16, v15, v14
	v_cmp_ge_f32_e64 s[0:1], 0, v17
	v_add_u32_e32 v17, 1, v15
	s_nop 0
	v_cndmask_b32_e64 v16, v15, v16, s[0:1]
	v_fma_f32 v15, -v17, v15, v14
	v_cmp_lt_f32_e64 s[0:1], 0, v15
	s_nop 1
	v_cndmask_b32_e64 v15, v16, v17, s[0:1]
	v_mul_f32_e32 v16, 0x37800000, v15
	v_cndmask_b32_e32 v15, v15, v16, vcc
	v_cmp_class_f32_e32 vcc, v14, v201
	s_nop 1
	v_cndmask_b32_e32 v14, v15, v14, vcc
	v_max_f32_e32 v40, 0x2b8cbccc, v14
	v_div_scale_f32 v209, s[0:1], v40, v40, 1.0
	v_rcp_f32_e32 v210, v209
	ds_read_b128 v[14:17], v171 offset:24576
	ds_read_b128 v[18:21], v205 offset:32064
	v_fma_f32 v211, -v209, v210, 1.0
	v_fmac_f32_e32 v210, v211, v210
	v_div_scale_f32 v211, vcc, 1.0, v40, 1.0
	v_mul_f32_e32 v212, v211, v210
	v_fma_f32 v213, -v209, v212, v211
	v_fmac_f32_e32 v212, v213, v210
	v_fma_f32 v209, -v209, v212, v211
	v_div_fmas_f32 v209, v209, v210, v212
	v_div_fixup_f32 v40, v209, v40, 1.0
	v_pk_mul_f32 v[210:211], v[116:117], v[40:41] op_sel_hi:[1,0]
	v_pk_mul_f32 v[212:213], v[118:119], v[40:41] op_sel_hi:[1,0]
	v_xor_b32_e32 v117, 0x80000000, v211
	v_xor_b32_e32 v116, 0x80000000, v210
	v_xor_b32_e32 v119, 0x80000000, v213
	v_xor_b32_e32 v118, 0x80000000, v212
	ds_write_b128 v171, v[116:119] offset:8192
	ds_read_b64 v[116:117], v205 offset:31808
	s_waitcnt lgkmcnt(3)
	v_pk_mul_f32 v[118:119], v[14:15], v[210:211]
	v_pk_add_f32 v[14:15], v[14:15], -1.0 op_sel_hi:[1,0]
	ds_write_b64 v171, v[118:119] offset:12288
	s_waitcnt lgkmcnt(1)
	v_pk_fma_f32 v[14:15], v[14:15], v[116:117], 1.0 op_sel_hi:[1,1,0]
	s_nop 0
	v_pk_mul_f32 v[12:13], v[12:13], v[14:15]
	ds_write_b64 v171, v[12:13] offset:4096
	ds_read_b64 v[14:15], v205 offset:31816
	v_pk_mul_f32 v[116:117], v[16:17], v[212:213]
	v_pk_add_f32 v[16:17], v[16:17], -1.0 op_sel_hi:[1,0]
	v_pk_mul_f32 v[8:9], v[8:9], v[12:13]
	ds_write_b64 v171, v[116:117] offset:12296
	s_waitcnt lgkmcnt(1)
	v_pk_fma_f32 v[14:15], v[16:17], v[14:15], 1.0 op_sel_hi:[1,1,0]
	v_mul_f32_e32 v12, v9, v19
	v_pk_mul_f32 v[14:15], v[22:23], v[14:15]
	v_fmac_f32_e32 v12, v8, v18
	v_pk_mul_f32 v[8:9], v[10:11], v[14:15]
	ds_write_b64 v171, v[14:15] offset:4104
	v_fmac_f32_e32 v12, v8, v20
	v_fmac_f32_e32 v12, v9, v21
	s_nop 1
	v_add_f32_dpp v8, v12, v12 row_ror:8 row_mask:0xf bank_mask:0xf bound_ctrl:1
	s_nop 1
	v_add_f32_dpp v8, v8, v8 row_ror:4 row_mask:0xf bank_mask:0xf bound_ctrl:1
	s_nop 1
	v_add_f32_dpp v8, v8, v8 row_ror:2 row_mask:0xf bank_mask:0xf bound_ctrl:1
	s_nop 1
	v_mov_b32_dpp v9, v8 row_ror:1 row_mask:0xf bank_mask:0xf bound_ctrl:1
	s_and_saveexec_b64 s[0:1], s[24:25]
	v_add_f32_e32 v8, v8, v9
	ds_write_b32 v163, v8 offset:28672
	s_or_b64 exec, exec, s[0:1]
	s_add_i32 s62, s28, 16
	s_cmpk_gt_u32 s28, 0x7ef
	s_cselect_b64 s[0:1], -1, 0
	s_and_b64 vcc, exec, s[0:1]
	s_cbranch_vccnz .LBB0_489
	v_add_u32_e32 v40, s62, v136
	v_lshl_add_u64 v[0:1], s[58:59], 0, v[40:41]
	v_mad_u64_u32 v[8:9], s[60:61], v0, s90, v[90:91]
	v_mad_i32_i24 v9, v1, s90, v9
	v_add_co_u32_e32 v2, vcc, 0x1000, v8
	v_lshlrev_b64 v[0:1], 9, v[0:1]
	s_nop 0
	v_addc_co_u32_e32 v3, vcc, 0, v9, vcc
	v_lshl_add_u64 v[4:5], v[42:43], 0, v[0:1]
	v_add_co_u32_e32 v10, vcc, 0xfffff000, v8
	global_load_dwordx2 v[76:77], v[8:9], off offset:2048
	global_load_dwordx2 v[86:87], v[2:3], off
	s_nop 0
	global_load_dwordx4 v[0:3], v[4:5], off offset:16
	s_nop 0
	global_load_dwordx4 v[4:7], v[4:5], off
	v_addc_co_u32_e32 v11, vcc, -1, v9, vcc
	global_load_dwordx2 v[88:89], v[8:9], off
	global_load_dwordx2 v[94:95], v[10:11], off offset:-2048
	global_load_dwordx2 v[96:97], v[8:9], off offset:-4096
	global_load_dwordx2 v[98:99], v[8:9], off offset:-2048

.LBB0_1005:
	v_lshlrev_b32_e32 v65, 2, v26
	global_load_dwordx4 v[156:159], v65, s[6:7]
	global_load_dwordx4 v[160:163], v65, s[6:7] offset:16
	global_load_dwordx4 v[164:167], v65, s[6:7] offset:32
	global_load_dwordx4 v[168:171], v65, s[6:7] offset:48
	global_load_dwordx4 v[172:175], v65, s[12:13]
	global_load_dwordx4 v[176:179], v65, s[12:13] offset:16
	global_load_dwordx4 v[180:183], v65, s[12:13] offset:32
	global_load_dwordx4 v[184:187], v65, s[12:13] offset:48
	global_load_dwordx4 v[188:191], v65, s[8:9]
	global_load_dwordx4 v[192:195], v65, s[8:9] offset:16
	global_load_dwordx4 v[196:199], v65, s[8:9] offset:32
	global_load_dwordx4 v[200:203], v65, s[8:9] offset:48
	global_load_dwordx4 v[204:207], v65, s[14:15]
	global_load_dwordx4 v[208:211], v65, s[14:15] offset:16
	global_load_dwordx4 v[212:215], v65, s[14:15] offset:32
	global_load_dwordx4 v[216:219], v65, s[14:15] offset:48
	v_add_co_u32_e32 v4, vcc, s4, v24
	v_lshl_add_u64 v[20:21], v[24:25], 0, s[22:23]
	s_nop 0
	v_addc_co_u32_e32 v5, vcc, 0, v25, vcc
	global_load_dwordx4 v[12:15], v[24:25], off offset:16
	global_load_dwordx4 v[16:19], v[24:25], off
	global_load_dwordx4 v[0:3], v[24:25], off offset:48
	global_load_dwordx4 v[8:11], v[24:25], off offset:32
	s_nop 0
	global_load_dwordx4 v[4:7], v[4:5], off
	s_nop 0
	global_load_dwordx4 v[32:35], v[20:21], off offset:32
	global_load_dwordx4 v[36:39], v[20:21], off offset:48
	s_nop 0
	global_load_dwordx4 v[20:23], v[20:21], off offset:16
	v_lshl_add_u64 v[134:135], v[134:135], 0, s[66:67]
	s_waitcnt vmcnt(7)
	v_mov_b32_e32 v31, v12
	s_waitcnt vmcnt(6)
	v_mov_b32_e32 v41, v16
	v_mov_b32_e32 v30, v19
	s_waitcnt vmcnt(1)
	v_mov_b32_e32 v40, v38
	v_mov_b32_e32 v38, v16
	v_pk_add_f32 v[38:39], v[40:41], v[38:39]
	s_nop 0
	v_not_b32_e32 v28, v39
	v_or_b32_e32 v40, 0x80000000, v39
	v_cmp_gt_i32_e32 vcc, 0, v38
	v_cmp_gt_i32_e64 s[0:1], 0, v39
	v_not_b32_e32 v39, v38
	v_or_b32_e32 v38, 0x80000000, v38
	v_cndmask_b32_e32 v38, v38, v39, vcc
	v_and_b32_e32 v38, 0xffffff00, v38
	v_cndmask_b32_e64 v28, v40, v28, s[0:1]
	v_or_b32_e32 v40, 0xf1, v38
	v_mov_b32_e32 v38, v37
	v_mov_b32_e32 v39, v16
	v_pk_mov_b32 v[36:37], v[38:39], v[36:37] op_sel:[1,0]
	v_and_b32_e32 v28, 0xffffff00, v28
	v_pk_add_f32 v[36:37], v[38:39], v[36:37]
	v_or_b32_e32 v28, 0xf0, v28
	v_not_b32_e32 v38, v37
	v_or_b32_e32 v39, 0x80000000, v37
	v_cmp_gt_i32_e64 s[0:1], 0, v37
	v_cmp_gt_i32_e32 vcc, 0, v36
	v_max_u32_e32 v41, v28, v40
	v_cndmask_b32_e64 v37, v39, v38, s[0:1]
	v_not_b32_e32 v38, v36
	v_or_b32_e32 v36, 0x80000000, v36
	v_cndmask_b32_e32 v36, v36, v38, vcc
	v_and_b32_e32 v37, 0xffffff00, v37
	v_and_b32_e32 v36, 0xffffff00, v36
	v_or_b32_e32 v37, 0xf3, v37
	v_or_b32_e32 v36, 0xf2, v36
	v_min_u32_e32 v38, v37, v36
	v_min_u32_e32 v28, v28, v40
	v_max_u32_e32 v40, v37, v36
	v_mov_b32_e32 v36, v33
	v_mov_b32_e32 v37, v16
	v_pk_mov_b32 v[32:33], v[36:37], v[32:33] op_sel:[1,0]
	v_max_u32_e32 v39, v41, v38
	v_pk_add_f32 v[32:33], v[36:37], v[32:33]
	v_max_u32_e32 v42, v28, v40
	v_not_b32_e32 v36, v33
	v_or_b32_e32 v37, 0x80000000, v33
	v_cmp_gt_i32_e64 s[0:1], 0, v33
	v_cmp_gt_i32_e32 vcc, 0, v32
	v_min_u32_e32 v38, v41, v38
	v_cndmask_b32_e64 v33, v37, v36, s[0:1]
	v_and_b32_e32 v33, 0xffffff00, v33
	v_or_b32_e32 v36, 0xf7, v33
	v_not_b32_e32 v33, v32
	v_or_b32_e32 v32, 0x80000000, v32
	v_cndmask_b32_e32 v32, v32, v33, vcc
	v_and_b32_e32 v32, 0xffffff00, v32
	v_or_b32_e32 v37, 0xf6, v32
	v_mov_b32_e32 v32, v34
	v_mov_b32_e32 v33, v16
	v_mov_b32_e32 v34, v16
	v_pk_add_f32 v[32:33], v[32:33], v[34:35]
	v_max_u32_e32 v44, v36, v37
	v_not_b32_e32 v34, v33
	v_or_b32_e32 v35, 0x80000000, v33
	v_cmp_gt_i32_e64 s[0:1], 0, v33
	v_cmp_gt_i32_e32 vcc, 0, v32
	v_min_u32_e32 v36, v36, v37
	v_cndmask_b32_e64 v33, v35, v34, s[0:1]
	v_not_b32_e32 v34, v32
	v_or_b32_e32 v32, 0x80000000, v32
	v_cndmask_b32_e32 v32, v32, v34, vcc
	v_and_b32_e32 v33, 0xffffff00, v33
	v_and_b32_e32 v32, 0xffffff00, v32
	v_or_b32_e32 v33, 0xf4, v33
	v_or_b32_e32 v32, 0xf5, v32
	v_min_u32_e32 v34, v33, v32
	v_max_u32_e32 v32, v33, v32
	v_min_u32_e32 v35, v44, v34
	v_min_u32_e32 v33, v36, v32
	v_min_u32_e32 v28, v28, v40
	v_max_u32_e32 v34, v44, v34
	v_max_u32_e32 v32, v36, v32
	v_max_u32_e32 v43, v39, v42
	v_min_u32_e32 v37, v35, v33
	v_max_u32_e32 v40, v38, v28
	v_min_u32_e32 v36, v34, v32
	v_min_u32_e32 v39, v39, v42
	v_max_u32_e32 v33, v35, v33
	v_min_u32_e32 v28, v38, v28
	v_max_u32_e32 v32, v34, v32
	v_min_u32_e32 v45, v43, v37
	v_min_u32_e32 v41, v40, v36
	v_min_u32_e32 v35, v39, v33
	v_min_u32_e32 v34, v28, v32
	v_max_u32_e32 v37, v43, v37
	v_max_u32_e32 v36, v40, v36
	v_max_u32_e32 v33, v39, v33
	v_max_u32_e32 v28, v28, v32
	v_min_u32_e32 v40, v37, v36
	v_min_u32_e32 v32, v33, v28
	v_min_u32_e32 v44, v45, v41
	v_min_u32_e32 v38, v35, v34
	v_min_u32_e32 v39, v40, v32
	v_max_u32_e32 v41, v45, v41
	v_max_u32_e32 v34, v35, v34
	v_max_u32_e32 v36, v37, v36
	v_max_u32_e32 v28, v33, v28
	v_max_u32_e32 v40, v40, v32
	s_waitcnt vmcnt(0)
	v_pk_add_f32 v[32:33], v[20:21], v[16:17] op_sel_hi:[1,0]
	v_min_u32_e32 v35, v41, v34
	v_min_u32_e32 v37, v36, v28
	v_max_u32_e32 v34, v41, v34
	v_max_u32_e32 v28, v36, v28
	v_not_b32_e32 v36, v32
	v_or_b32_e32 v41, 0x80000000, v32
	v_cmp_gt_i32_e64 s[0:1], 0, v32
	v_cmp_gt_i32_e32 vcc, 0, v33
	v_min_u32_e32 v42, v44, v38
	v_cndmask_b32_e64 v32, v41, v36, s[0:1]
	v_not_b32_e32 v36, v33
	v_or_b32_e32 v33, 0x80000000, v33
	v_cndmask_b32_e32 v33, v33, v36, vcc
	v_and_b32_e32 v32, 0xffffff00, v32
	v_and_b32_e32 v33, 0xffffff00, v33
	v_or_b32_e32 v32, 0xfb, v32
	v_or_b32_e32 v33, 0xfa, v33
	v_min_u32_e32 v36, v32, v33
	v_max_u32_e32 v41, v32, v33
	v_pk_add_f32 v[32:33], v[16:17], v[20:21] op_sel:[1,0]
	v_max_u32_e32 v38, v44, v38
	v_not_b32_e32 v21, v32
	v_or_b32_e32 v43, 0x80000000, v32
	v_cmp_gt_i32_e32 vcc, 0, v33
	v_cmp_gt_i32_e64 s[0:1], 0, v32
	v_not_b32_e32 v32, v33
	v_or_b32_e32 v33, 0x80000000, v33
	v_cndmask_b32_e32 v32, v33, v32, vcc
	v_and_b32_e32 v32, 0xffffff00, v32
	v_cndmask_b32_e64 v21, v43, v21, s[0:1]
	v_or_b32_e32 v43, 0xea, v32
	v_pk_add_f32 v[32:33], v[22:23], v[16:17] op_sel_hi:[1,0]
	v_pk_add_f32 v[22:23], v[16:17], v[22:23] op_sel:[1,0]
	v_not_b32_e32 v44, v33
	v_or_b32_e32 v45, 0x80000000, v33
	v_cmp_gt_i32_e64 s[0:1], 0, v33
	v_cmp_gt_i32_e32 vcc, 0, v32
	v_and_b32_e32 v21, 0xffffff00, v21
	v_cndmask_b32_e64 v33, v45, v44, s[0:1]
	v_not_b32_e32 v44, v32
	v_or_b32_e32 v32, 0x80000000, v32
	v_cndmask_b32_e32 v32, v32, v44, vcc
	v_and_b32_e32 v33, 0xffffff00, v33
	v_and_b32_e32 v32, 0xffffff00, v32
	v_or_b32_e32 v33, 0xf8, v33
	v_or_b32_e32 v32, 0xf9, v32
	v_max_u32_e32 v44, v33, v32
	v_min_u32_e32 v32, v33, v32
	v_min_u32_e32 v45, v44, v36
	v_min_u32_e32 v33, v32, v41
	v_max_u32_e32 v36, v44, v36
	v_max_u32_e32 v32, v32, v41
	v_min_u32_e32 v41, v36, v32
	v_max_u32_e32 v32, v36, v32
	v_not_b32_e32 v36, v22
	v_or_b32_e32 v44, 0x80000000, v22
	v_cmp_gt_i32_e64 s[0:1], 0, v22
	v_cmp_gt_i32_e32 vcc, 0, v23
	v_min_u32_e32 v46, v45, v33
	v_cndmask_b32_e64 v22, v44, v36, s[0:1]
	v_and_b32_e32 v22, 0xffffff00, v22
	v_or_b32_e32 v36, 0xe9, v22
	v_not_b32_e32 v22, v23
	v_or_b32_e32 v23, 0x80000000, v23
	v_cndmask_b32_e32 v22, v23, v22, vcc
	v_and_b32_e32 v22, 0xffffff00, v22
	v_or_b32_e32 v44, 0xe8, v22
	v_pk_add_f32 v[22:23], v[6:7], v[16:17] op_sel_hi:[1,0]
	v_max_u32_e32 v33, v45, v33
	v_not_b32_e32 v45, v23
	v_or_b32_e32 v47, 0x80000000, v23
	v_cmp_gt_i32_e64 s[0:1], 0, v23
	v_cmp_gt_i32_e32 vcc, 0, v22
	v_or_b32_e32 v21, 0xeb, v21
	v_cndmask_b32_e64 v23, v47, v45, s[0:1]
	v_not_b32_e32 v45, v22
	v_or_b32_e32 v22, 0x80000000, v22
	v_cndmask_b32_e32 v22, v22, v45, vcc
	v_and_b32_e32 v23, 0xffffff00, v23
	v_and_b32_e32 v22, 0xffffff00, v22
	v_or_b32_e32 v23, 0xfc, v23
	v_or_b32_e32 v22, 0xfd, v22
	v_min_u32_e32 v45, v23, v22
	v_max_u32_e32 v47, v23, v22
	v_pk_add_f32 v[22:23], v[16:17], v[6:7] op_sel:[1,0]
	s_nop 0
	v_not_b32_e32 v48, v22
	v_or_b32_e32 v49, 0x80000000, v22
	v_cmp_gt_i32_e64 s[0:1], 0, v22
	v_cmp_gt_i32_e32 vcc, 0, v23
	s_nop 0
	v_cndmask_b32_e64 v22, v49, v48, s[0:1]
	v_and_b32_e32 v22, 0xffffff00, v22
	v_or_b32_e32 v48, 0xed, v22
	v_not_b32_e32 v22, v23
	v_or_b32_e32 v23, 0x80000000, v23
	v_cndmask_b32_e32 v22, v23, v22, vcc
	v_and_b32_e32 v22, 0xffffff00, v22
	v_or_b32_e32 v49, 0xec, v22
	v_pk_add_f32 v[22:23], v[18:19], v[6:7] op_sel_hi:[0,1]
	v_not_b32_e32 v50, v22
	v_or_b32_e32 v51, 0x80000000, v22
	v_cmp_gt_i32_e64 s[0:1], 0, v22
	v_cmp_gt_i32_e32 vcc, 0, v23
	s_nop 0
	v_cndmask_b32_e64 v22, v51, v50, s[0:1]
	v_and_b32_e32 v22, 0xffffff00, v22
	v_or_b32_e32 v50, 0xdd, v22
	v_not_b32_e32 v22, v23
	v_or_b32_e32 v23, 0x80000000, v23
	v_cndmask_b32_e32 v22, v23, v22, vcc
	v_and_b32_e32 v22, 0xffffff00, v22
	v_or_b32_e32 v51, 0xdc, v22
	v_pk_add_f32 v[22:23], v[4:5], v[16:17] op_sel_hi:[1,0]
	v_pk_add_f32 v[16:17], v[16:17], v[4:5] op_sel:[1,0]
	v_not_b32_e32 v52, v22
	v_or_b32_e32 v53, 0x80000000, v22
	v_cmp_gt_i32_e64 s[0:1], 0, v22
	v_cmp_gt_i32_e32 vcc, 0, v23
	v_or_b32_e32 v67, 0x80000000, v16
	v_cndmask_b32_e64 v22, v53, v52, s[0:1]
	v_not_b32_e32 v52, v23
	v_or_b32_e32 v23, 0x80000000, v23
	v_cndmask_b32_e32 v23, v23, v52, vcc
	v_and_b32_e32 v23, 0xffffff00, v23
	v_or_b32_e32 v22, 0xff, v22
	v_or_b32_e32 v23, 0xfe, v23
	v_max_u32_e32 v52, v22, v23
	v_min_u32_e32 v22, v22, v23
	v_max_u32_e32 v53, v52, v45
	v_max_u32_e32 v23, v22, v47
	v_min_u32_e32 v45, v52, v45
	v_min_u32_e32 v22, v22, v47
	v_max_u32_e32 v54, v53, v23
	v_max_u32_e32 v47, v45, v22
	v_min_u32_e32 v23, v53, v23
	v_min_u32_e32 v22, v45, v22
	v_max_u32_e32 v55, v54, v46
	v_max_u32_e32 v52, v47, v41
	v_max_u32_e32 v53, v23, v33
	v_max_u32_e32 v45, v22, v32
	v_min_u32_e32 v46, v54, v46
	v_min_u32_e32 v41, v47, v41
	v_min_u32_e32 v23, v23, v33
	v_min_u32_e32 v22, v22, v32
	v_max_u32_e32 v56, v55, v52
	v_max_u32_e32 v57, v53, v45
	v_max_u32_e32 v47, v46, v41
	v_max_u32_e32 v32, v23, v22
	v_min_u32_e32 v52, v55, v52
	v_min_u32_e32 v45, v53, v45
	v_min_u32_e32 v41, v46, v41
	v_min_u32_e32 v22, v23, v22
	v_max_u32_e32 v58, v56, v57
	v_max_u32_e32 v33, v47, v32
	v_max_u32_e32 v53, v52, v45
	v_max_u32_e32 v23, v41, v22
	v_min_u32_e32 v56, v56, v57
	v_min_u32_e32 v32, v47, v32
	v_min_u32_e32 v45, v52, v45
	v_min_u32_e32 v22, v41, v22
	v_min_u32_e32 v59, v58, v42
	v_min_u32_e32 v54, v33, v39
	v_min_u32_e32 v55, v53, v35
	v_min_u32_e32 v46, v23, v37
	v_min_u32_e32 v57, v56, v38
	v_min_u32_e32 v47, v32, v40
	v_min_u32_e32 v52, v45, v34
	v_min_u32_e32 v41, v22, v28
	v_min_u32_e32 v60, v59, v54
	v_min_u32_e32 v61, v55, v46
	v_min_u32_e32 v63, v57, v47
	v_min_u32_e32 v64, v52, v41
	v_min_u32_e32 v62, v60, v61
	v_min_u32_e32 v65, v63, v64
	v_min_u32_e32 v66, v62, v65
	v_max_u32_e32 v42, v58, v42
	v_max_u32_e32 v33, v33, v39
	v_max_u32_e32 v35, v53, v35
	v_max_u32_e32 v23, v23, v37
	v_max_u32_e32 v38, v56, v38
	v_max_u32_e32 v32, v32, v40
	v_max_u32_e32 v34, v45, v34
	v_max_u32_e32 v22, v22, v28
	v_max_u32_e32 v62, v62, v65
	v_not_b32_e32 v65, v16
	v_cmp_gt_i32_e64 s[0:1], 0, v16
	v_max_u32_e32 v39, v42, v33
	v_max_u32_e32 v37, v35, v23
	v_max_u32_e32 v40, v38, v32
	v_max_u32_e32 v28, v34, v22
	v_cndmask_b32_e64 v16, v67, v65, s[0:1]
	v_max_u32_e32 v53, v39, v37
	v_max_u32_e32 v45, v40, v28
	v_and_b32_e32 v16, 0xffffff00, v16
	v_max_u32_e32 v56, v53, v45
	v_or_b32_e32 v16, 0xef, v16
	v_min_u32_e32 v58, v53, v45
	v_min_u32_e32 v37, v39, v37
	v_min_u32_e32 v28, v40, v28
	v_max_u32_e32 v65, v56, v16
	v_min_u32_e32 v56, v56, v16
	v_max_u32_e32 v39, v37, v28
	v_min_u32_e32 v33, v42, v33
	v_min_u32_e32 v23, v35, v23
	v_min_u32_e32 v32, v38, v32
	v_min_u32_e32 v22, v34, v22
	v_med3_u32 v16, v53, v45, v16
	v_min_u32_e32 v45, v58, v56
	v_min_u32_e32 v40, v37, v28
	v_max_u32_e32 v35, v33, v23
	v_max_u32_e32 v34, v32, v22
	v_max_u32_e32 v53, v39, v45
	v_min_u32_e32 v39, v39, v45
	v_max_u32_e32 v38, v35, v34
	v_med3_u32 v28, v37, v28, v45
	v_min_u32_e32 v37, v40, v39
	v_min_u32_e32 v42, v35, v34
	v_min_u32_e32 v23, v33, v23
	v_min_u32_e32 v22, v32, v22
	v_max_u32_e32 v39, v38, v37
	v_min_u32_e32 v38, v38, v37
	v_max_u32_e32 v32, v23, v22
	v_max_u32_e32 v54, v59, v54
	v_max_u32_e32 v46, v55, v46
	v_max_u32_e32 v47, v57, v47
	v_max_u32_e32 v41, v52, v41
	v_cmp_gt_i32_e32 vcc, 0, v17
	v_med3_u32 v34, v35, v34, v37
	v_min_u32_e32 v35, v42, v38
	v_not_b32_e32 v45, v17
	v_or_b32_e32 v17, 0x80000000, v17
	v_min_u32_e32 v33, v23, v22
	v_max_u32_e32 v55, v54, v46
	v_max_u32_e32 v52, v47, v41
	v_max_u32_e32 v37, v32, v35
	v_min_u32_e32 v32, v32, v35
	v_cndmask_b32_e32 v17, v17, v45, vcc
	v_max_u32_e32 v57, v55, v52
	v_med3_u32 v22, v23, v22, v35
	v_min_u32_e32 v23, v33, v32
	v_and_b32_e32 v17, 0xffffff00, v17
	v_min_u32_e32 v59, v55, v52
	v_min_u32_e32 v46, v54, v46
	v_min_u32_e32 v41, v47, v41
	v_min_u32_e32 v33, v57, v23
	v_or_b32_e32 v17, 0xee, v17
	v_max_u32_e32 v47, v46, v41
	v_min_u32_e32 v33, v59, v33
	v_max_u32_e32 v45, v65, v17
	v_min_u32_e32 v17, v65, v17
	v_min_u32_e32 v54, v46, v41
	v_max_u32_e32 v35, v47, v33
	v_min_u32_e32 v38, v47, v33
	v_med3_u32 v33, v46, v41, v33
	v_max_u32_e32 v46, v16, v17
	v_min_u32_e32 v16, v16, v17
	v_max_u32_e32 v17, v53, v16
	v_min_u32_e32 v16, v53, v16
	v_max_u32_e32 v47, v28, v16
	v_min_u32_e32 v16, v28, v16
	v_max_u32_e32 v28, v39, v16
	v_min_u32_e32 v16, v39, v16
	v_max_u32_e32 v39, v34, v16
	v_min_u32_e32 v16, v34, v16
	v_max_u32_e32 v34, v37, v16
	v_min_u32_e32 v16, v37, v16
	v_max_u32_e32 v32, v57, v23
	v_max_u32_e32 v37, v22, v16
	v_min_u32_e32 v16, v22, v16
	v_med3_u32 v23, v55, v52, v23
	v_max_u32_e32 v22, v32, v16
	v_min_u32_e32 v16, v32, v16
	v_max_u32_e32 v60, v60, v61
	v_max_u32_e32 v61, v63, v64
	v_max_u32_e32 v32, v23, v16
	v_min_u32_e32 v16, v23, v16
	v_max_u32_e32 v63, v60, v61
	v_min_u32_e32 v38, v54, v38
	v_max_u32_e32 v23, v35, v16
	v_min_u32_e32 v16, v35, v16
	v_min_u32_e32 v64, v60, v61
	v_max_u32_e32 v40, v63, v38
	v_min_u32_e32 v41, v63, v38
	v_max_u32_e32 v35, v33, v16
	v_min_u32_e32 v16, v33, v16
	v_med3_u32 v38, v60, v61, v38
	v_min_u32_e32 v41, v64, v41
	v_max_u32_e32 v33, v40, v16
	v_min_u32_e32 v16, v40, v16
	v_max_u32_e32 v42, v62, v41
	v_max_u32_e32 v40, v38, v16
	v_min_u32_e32 v16, v38, v16
	v_min_u32_e32 v41, v62, v41
	v_max_u32_e32 v38, v42, v16
	v_min_u32_e32 v16, v42, v16
	v_min_u32_e32 v42, v45, v48
	v_max3_u32 v16, v66, v41, v16
	v_max_u32_e32 v41, v45, v48
	v_max_u32_e32 v45, v46, v42
	v_min_u32_e32 v42, v46, v42
	v_max_u32_e32 v46, v17, v42
	v_min_u32_e32 v17, v17, v42
	v_max_u32_e32 v42, v47, v17
	v_min_u32_e32 v17, v47, v17
	v_max_u32_e32 v47, v28, v17
	v_min_u32_e32 v17, v28, v17
	v_max_u32_e32 v28, v39, v17
	v_min_u32_e32 v17, v39, v17
	v_max_u32_e32 v39, v34, v17
	v_min_u32_e32 v17, v34, v17
	v_max_u32_e32 v34, v37, v17
	v_min_u32_e32 v17, v37, v17
	v_max_u32_e32 v37, v22, v17
	v_min_u32_e32 v17, v22, v17
	v_max_u32_e32 v22, v32, v17
	v_min_u32_e32 v17, v32, v17
	v_max_u32_e32 v32, v23, v17
	v_min_u32_e32 v17, v23, v17
	v_max_u32_e32 v23, v35, v17
	v_min_u32_e32 v17, v35, v17
	v_max_u32_e32 v35, v33, v17
	v_min_u32_e32 v17, v33, v17
	v_max_u32_e32 v33, v40, v17
	v_min_u32_e32 v17, v40, v17
	v_max_u32_e32 v40, v38, v17
	v_min_u32_e32 v17, v38, v17
	v_max_u32_e32 v38, v41, v49
	v_min_u32_e32 v41, v41, v49
	v_max_u32_e32 v48, v45, v41
	v_min_u32_e32 v41, v45, v41
	v_max_u32_e32 v45, v46, v41
	v_min_u32_e32 v41, v46, v41
	v_max_u32_e32 v46, v42, v41
	v_min_u32_e32 v41, v42, v41
	v_max_u32_e32 v42, v47, v41
	v_min_u32_e32 v41, v47, v41
	v_max_u32_e32 v47, v28, v41
	v_min_u32_e32 v28, v28, v41
	v_max_u32_e32 v41, v39, v28
	v_min_u32_e32 v28, v39, v28
	v_max_u32_e32 v39, v34, v28
	v_min_u32_e32 v28, v34, v28
	v_max_u32_e32 v34, v37, v28
	v_min_u32_e32 v28, v37, v28
	v_max_u32_e32 v37, v22, v28
	v_min_u32_e32 v22, v22, v28
	v_max_u32_e32 v28, v32, v22
	v_min_u32_e32 v22, v32, v22
	v_max_u32_e32 v32, v23, v22
	v_min_u32_e32 v22, v23, v22
	v_max_u32_e32 v23, v35, v22
	v_min_u32_e32 v22, v35, v22
	v_max_u32_e32 v35, v33, v22
	v_min_u32_e32 v22, v33, v22
	v_max_u32_e32 v33, v40, v22
	v_min_u32_e32 v22, v40, v22
	v_max3_u32 v16, v16, v17, v22
	v_max_u32_e32 v17, v38, v21
	v_min_u32_e32 v21, v38, v21
	v_max_u32_e32 v22, v48, v21
	v_min_u32_e32 v21, v48, v21
	v_max_u32_e32 v38, v45, v21
	v_min_u32_e32 v21, v45, v21
	v_max_u32_e32 v40, v46, v21
	v_min_u32_e32 v21, v46, v21
	v_max_u32_e32 v45, v42, v21
	v_min_u32_e32 v21, v42, v21
	v_max_u32_e32 v42, v47, v21
	v_min_u32_e32 v21, v47, v21
	v_max_u32_e32 v46, v41, v21
	v_min_u32_e32 v21, v41, v21
	v_max_u32_e32 v41, v39, v21
	v_min_u32_e32 v21, v39, v21
	v_max_u32_e32 v39, v34, v21
	v_min_u32_e32 v21, v34, v21
	v_max_u32_e32 v34, v37, v21
	v_min_u32_e32 v21, v37, v21
	v_max_u32_e32 v37, v28, v21
	v_min_u32_e32 v21, v28, v21
	v_max_u32_e32 v28, v32, v21
	v_min_u32_e32 v21, v32, v21
	v_max_u32_e32 v32, v23, v21
	v_min_u32_e32 v21, v23, v21
	v_max_u32_e32 v23, v35, v21
	v_min_u32_e32 v21, v35, v21
	v_max_u32_e32 v35, v33, v21
	v_min_u32_e32 v21, v33, v21
	v_max_u32_e32 v33, v17, v43
	v_min_u32_e32 v17, v17, v43
	v_max_u32_e32 v43, v22, v17
	v_min_u32_e32 v17, v22, v17
	v_max_u32_e32 v22, v38, v17
	v_min_u32_e32 v17, v38, v17
	v_max_u32_e32 v38, v40, v17
	v_min_u32_e32 v17, v40, v17
	v_max_u32_e32 v40, v45, v17
	v_min_u32_e32 v17, v45, v17
	v_max_u32_e32 v45, v42, v17
	v_min_u32_e32 v17, v42, v17
	v_max_u32_e32 v42, v46, v17
	v_min_u32_e32 v17, v46, v17
	v_max_u32_e32 v46, v41, v17
	v_min_u32_e32 v17, v41, v17
	v_max_u32_e32 v41, v39, v17
	v_min_u32_e32 v17, v39, v17
	v_max_u32_e32 v39, v34, v17
	v_min_u32_e32 v17, v34, v17
	v_max_u32_e32 v34, v37, v17
	v_min_u32_e32 v17, v37, v17
	v_max_u32_e32 v37, v28, v17
	v_min_u32_e32 v17, v28, v17
	v_max_u32_e32 v28, v32, v17
	v_min_u32_e32 v17, v32, v17
	v_max_u32_e32 v32, v23, v17
	v_min_u32_e32 v17, v23, v17
	v_max_u32_e32 v23, v35, v17
	v_min_u32_e32 v17, v35, v17
	v_max3_u32 v16, v16, v21, v17
	v_min_u32_e32 v21, v33, v36
	v_max_u32_e32 v17, v33, v36
	v_max_u32_e32 v33, v43, v21
	v_min_u32_e32 v21, v43, v21
	v_max_u32_e32 v35, v22, v21
	v_min_u32_e32 v21, v22, v21
	v_max_u32_e32 v22, v38, v21
	v_min_u32_e32 v21, v38, v21
	v_max_u32_e32 v36, v40, v21
	v_min_u32_e32 v21, v40, v21
	v_max_u32_e32 v38, v45, v21
	v_min_u32_e32 v21, v45, v21
	v_max_u32_e32 v40, v42, v21
	v_min_u32_e32 v21, v42, v21
	v_max_u32_e32 v42, v46, v21
	v_min_u32_e32 v21, v46, v21
	v_max_u32_e32 v43, v41, v21
	v_min_u32_e32 v21, v41, v21
	v_max_u32_e32 v41, v39, v21
	v_min_u32_e32 v21, v39, v21
	v_max_u32_e32 v39, v34, v21
	v_min_u32_e32 v21, v34, v21
	v_max_u32_e32 v34, v37, v21
	v_min_u32_e32 v21, v37, v21
	v_max_u32_e32 v37, v28, v21
	v_min_u32_e32 v21, v28, v21
	v_max_u32_e32 v28, v32, v21
	v_min_u32_e32 v21, v32, v21
	v_max_u32_e32 v32, v23, v21
	v_min_u32_e32 v21, v23, v21
	v_max_u32_e32 v23, v17, v44
	v_min_u32_e32 v17, v17, v44
	v_max_u32_e32 v44, v33, v17
	v_min_u32_e32 v17, v33, v17
	v_max_u32_e32 v33, v35, v17
	v_min_u32_e32 v17, v35, v17
	v_max_u32_e32 v35, v22, v17
	v_min_u32_e32 v17, v22, v17
	v_max_u32_e32 v22, v36, v17
	v_min_u32_e32 v17, v36, v17
	v_max_u32_e32 v36, v38, v17
	v_min_u32_e32 v17, v38, v17
	v_max_u32_e32 v38, v40, v17
	v_min_u32_e32 v17, v40, v17
	v_max_u32_e32 v40, v42, v17
	v_min_u32_e32 v17, v42, v17
	v_max_u32_e32 v42, v43, v17
	v_min_u32_e32 v17, v43, v17
	v_max_u32_e32 v43, v41, v17
	v_min_u32_e32 v17, v41, v17
	v_max_u32_e32 v41, v39, v17
	v_min_u32_e32 v17, v39, v17
	v_max_u32_e32 v39, v34, v17
	v_min_u32_e32 v17, v34, v17
	v_max_u32_e32 v34, v37, v17
	v_min_u32_e32 v17, v37, v17
	v_max_u32_e32 v37, v28, v17
	v_min_u32_e32 v17, v28, v17
	v_max_u32_e32 v28, v32, v17
	v_min_u32_e32 v17, v32, v17
	v_max3_u32 v21, v16, v21, v17
	v_pk_add_f32 v[16:17], v[18:19], v[4:5] op_sel_hi:[0,1]
	v_not_b32_e32 v32, v16
	v_or_b32_e32 v45, 0x80000000, v16
	v_cmp_gt_i32_e64 s[0:1], 0, v16
	v_cmp_gt_i32_e32 vcc, 0, v17
	s_nop 0
	v_cndmask_b32_e64 v16, v45, v32, s[0:1]
	v_and_b32_e32 v16, 0xffffff00, v16
	v_or_b32_e32 v16, 0xdf, v16
	v_max_u32_e32 v32, v23, v16
	v_min_u32_e32 v16, v23, v16
	v_max_u32_e32 v23, v44, v16
	v_min_u32_e32 v16, v44, v16
	v_max_u32_e32 v44, v33, v16
	v_min_u32_e32 v16, v33, v16
	v_max_u32_e32 v33, v35, v16
	v_min_u32_e32 v16, v35, v16
	v_max_u32_e32 v35, v22, v16
	v_min_u32_e32 v16, v22, v16
	v_max_u32_e32 v22, v36, v16
	v_min_u32_e32 v16, v36, v16
	v_max_u32_e32 v36, v38, v16
	v_min_u32_e32 v16, v38, v16
	v_max_u32_e32 v38, v40, v16
	v_min_u32_e32 v16, v40, v16
	v_max_u32_e32 v40, v42, v16
	v_min_u32_e32 v16, v42, v16
	v_max_u32_e32 v42, v43, v16
	v_min_u32_e32 v16, v43, v16
	v_max_u32_e32 v43, v41, v16
	v_min_u32_e32 v16, v41, v16
	v_max_u32_e32 v41, v39, v16
	v_min_u32_e32 v16, v39, v16
	v_max_u32_e32 v39, v34, v16
	v_min_u32_e32 v16, v34, v16
	v_max_u32_e32 v34, v37, v16
	v_min_u32_e32 v16, v37, v16
	v_max_u32_e32 v37, v28, v16
	v_min_u32_e32 v16, v28, v16
	v_not_b32_e32 v28, v17
	v_or_b32_e32 v17, 0x80000000, v17
	v_cndmask_b32_e32 v17, v17, v28, vcc
	v_and_b32_e32 v17, 0xffffff00, v17
	v_or_b32_e32 v17, 0xde, v17
	v_max_u32_e32 v28, v32, v17
	v_min_u32_e32 v17, v32, v17
	v_max_u32_e32 v32, v23, v17
	v_min_u32_e32 v17, v23, v17
	v_max_u32_e32 v23, v44, v17
	v_min_u32_e32 v17, v44, v17
	v_max_u32_e32 v44, v33, v17
	v_min_u32_e32 v17, v33, v17
	v_max_u32_e32 v33, v35, v17
	v_min_u32_e32 v17, v35, v17
	v_max_u32_e32 v35, v22, v17
	v_min_u32_e32 v17, v22, v17
	v_max_u32_e32 v22, v36, v17
	v_min_u32_e32 v17, v36, v17
	v_max_u32_e32 v36, v38, v17
	v_min_u32_e32 v17, v38, v17
	v_max_u32_e32 v38, v40, v17
	v_min_u32_e32 v17, v40, v17
	v_max_u32_e32 v40, v42, v17
	v_min_u32_e32 v17, v42, v17
	v_max_u32_e32 v42, v43, v17
	v_min_u32_e32 v17, v43, v17
	v_max_u32_e32 v43, v41, v17
	v_min_u32_e32 v17, v41, v17
	v_max_u32_e32 v41, v39, v17
	v_min_u32_e32 v17, v39, v17
	v_max_u32_e32 v39, v34, v17
	v_min_u32_e32 v17, v34, v17
	v_max_u32_e32 v34, v37, v17
	v_min_u32_e32 v17, v37, v17
	v_max3_u32 v16, v21, v16, v17
	v_min_u32_e32 v21, v28, v50
	v_max_u32_e32 v17, v28, v50
	v_max_u32_e32 v28, v32, v21
	v_min_u32_e32 v21, v32, v21
	v_max_u32_e32 v32, v23, v21
	v_min_u32_e32 v21, v23, v21
	v_max_u32_e32 v23, v44, v21
	v_min_u32_e32 v21, v44, v21
	v_max_u32_e32 v37, v33, v21
	v_min_u32_e32 v21, v33, v21
	v_max_u32_e32 v33, v35, v21
	v_min_u32_e32 v21, v35, v21
	v_max_u32_e32 v35, v22, v21
	v_min_u32_e32 v21, v22, v21
	v_max_u32_e32 v22, v36, v21
	v_min_u32_e32 v21, v36, v21
	v_max_u32_e32 v36, v38, v21
	v_min_u32_e32 v21, v38, v21
	v_max_u32_e32 v38, v40, v21
	v_min_u32_e32 v21, v40, v21
	v_max_u32_e32 v40, v42, v21
	v_min_u32_e32 v21, v42, v21
	v_max_u32_e32 v42, v43, v21
	v_min_u32_e32 v21, v43, v21
	v_max_u32_e32 v43, v41, v21
	v_min_u32_e32 v21, v41, v21
	v_max_u32_e32 v41, v39, v21
	v_min_u32_e32 v21, v39, v21
	v_max_u32_e32 v39, v34, v21
	v_min_u32_e32 v21, v34, v21
	v_max_u32_e32 v34, v17, v51
	v_min_u32_e32 v17, v17, v51
	v_max_u32_e32 v44, v28, v17
	v_min_u32_e32 v17, v28, v17
	v_max_u32_e32 v28, v32, v17
	v_min_u32_e32 v17, v32, v17
	v_max_u32_e32 v32, v23, v17
	v_min_u32_e32 v17, v23, v17
	v_max_u32_e32 v45, v37, v17
	v_min_u32_e32 v17, v37, v17
	v_max_u32_e32 v37, v33, v17
	v_min_u32_e32 v17, v33, v17
	v_max_u32_e32 v33, v35, v17
	v_min_u32_e32 v17, v35, v17
	v_max_u32_e32 v35, v22, v17
	v_min_u32_e32 v17, v22, v17
	v_max_u32_e32 v46, v36, v17
	v_min_u32_e32 v17, v36, v17
	v_max_u32_e32 v36, v38, v17
	v_min_u32_e32 v17, v38, v17
	v_max_u32_e32 v38, v40, v17
	v_min_u32_e32 v17, v40, v17
	v_max_u32_e32 v40, v42, v17
	v_min_u32_e32 v17, v42, v17
	v_max_u32_e32 v42, v43, v17
	v_min_u32_e32 v17, v43, v17
	v_max_u32_e32 v43, v41, v17
	v_min_u32_e32 v17, v41, v17
	v_max_u32_e32 v41, v39, v17
	v_min_u32_e32 v17, v39, v17
	v_max3_u32 v39, v16, v21, v17
	v_pk_mov_b32 v[16:17], v[6:7], v[4:5] op_sel:[1,0]
	v_mov_b32_e32 v22, v19
	v_pk_add_f32 v[16:17], v[16:17], v[30:31]
	v_mov_b32_e32 v23, v18
	v_not_b32_e32 v7, v16
	v_or_b32_e32 v21, 0x80000000, v16
	v_cmp_gt_i32_e64 s[0:1], 0, v16
	v_mov_b32_e32 v30, v4
	v_mov_b32_e32 v31, v20
	v_cndmask_b32_e64 v7, v21, v7, s[0:1]
	v_and_b32_e32 v7, 0xffffff00, v7
	v_pk_add_f32 v[20:21], v[22:23], v[30:31]
	v_or_b32_e32 v47, 0xcc, v7
	v_not_b32_e32 v7, v21
	v_or_b32_e32 v16, 0x80000000, v21
	v_cmp_gt_i32_e64 s[2:3], 0, v21
	v_cmp_gt_i32_e64 s[0:1], 0, v20
	v_cmp_gt_i32_e32 vcc, 0, v17
	v_cndmask_b32_e64 v7, v16, v7, s[2:3]
	v_and_b32_e32 v7, 0xffffff00, v7
	v_or_b32_e32 v7, 0xdb, v7
	v_max_u32_e32 v16, v34, v7
	v_min_u32_e32 v7, v34, v7
	v_max_u32_e32 v18, v44, v7
	v_min_u32_e32 v7, v44, v7
	v_max_u32_e32 v21, v28, v7
	v_min_u32_e32 v7, v28, v7
	v_max_u32_e32 v22, v32, v7
	v_min_u32_e32 v7, v32, v7
	v_max_u32_e32 v23, v45, v7
	v_min_u32_e32 v7, v45, v7
	v_max_u32_e32 v28, v37, v7
	v_min_u32_e32 v7, v37, v7
	v_max_u32_e32 v30, v33, v7
	v_min_u32_e32 v7, v33, v7
	v_max_u32_e32 v31, v35, v7
	v_min_u32_e32 v7, v35, v7
	v_max_u32_e32 v32, v46, v7
	v_min_u32_e32 v7, v46, v7
	v_max_u32_e32 v33, v36, v7
	v_min_u32_e32 v7, v36, v7
	v_max_u32_e32 v34, v38, v7
	v_min_u32_e32 v7, v38, v7
	v_max_u32_e32 v35, v40, v7
	v_min_u32_e32 v7, v40, v7
	v_not_b32_e32 v40, v20
	v_or_b32_e32 v20, 0x80000000, v20
	v_cndmask_b32_e64 v20, v20, v40, s[0:1]
	v_and_b32_e32 v20, 0xffffff00, v20
	v_or_b32_e32 v20, 0xcf, v20
	v_max_u32_e32 v36, v42, v7
	v_min_u32_e32 v7, v42, v7
	v_max_u32_e32 v40, v16, v20
	v_min_u32_e32 v16, v16, v20
	v_max_u32_e32 v37, v43, v7
	v_min_u32_e32 v7, v43, v7
	v_max_u32_e32 v20, v18, v16
	v_min_u32_e32 v16, v18, v16
	v_max_u32_e32 v38, v41, v7
	v_min_u32_e32 v7, v41, v7
	v_max_u32_e32 v41, v21, v16
	v_min_u32_e32 v16, v21, v16
	v_max_u32_e32 v21, v22, v16
	v_min_u32_e32 v16, v22, v16
	v_max_u32_e32 v22, v23, v16
	v_min_u32_e32 v16, v23, v16
	v_max_u32_e32 v23, v28, v16
	v_min_u32_e32 v16, v28, v16
	v_max_u32_e32 v28, v30, v16
	v_min_u32_e32 v16, v30, v16
	v_max_u32_e32 v30, v31, v16
	v_min_u32_e32 v16, v31, v16
	v_max_u32_e32 v31, v32, v16
	v_min_u32_e32 v16, v32, v16
	v_max_u32_e32 v32, v33, v16
	v_min_u32_e32 v16, v33, v16
	v_max_u32_e32 v33, v34, v16
	v_min_u32_e32 v16, v34, v16
	v_max_u32_e32 v34, v35, v16
	v_min_u32_e32 v16, v35, v16
	v_max_u32_e32 v35, v36, v16
	v_min_u32_e32 v16, v36, v16
	v_max_u32_e32 v36, v37, v16
	v_min_u32_e32 v16, v37, v16
	v_max_u32_e32 v37, v38, v16
	v_min_u32_e32 v16, v38, v16
	v_max3_u32 v38, v39, v7, v16
	v_mov_b32_e32 v16, v19
	v_mov_b32_e32 v7, v5
	v_pk_add_f32 v[18:19], v[16:17], v[6:7] op_sel_hi:[0,1]
	v_not_b32_e32 v16, v18
	v_or_b32_e32 v39, 0x80000000, v18
	v_cmp_gt_i32_e64 s[0:1], 0, v19
	v_cmp_gt_i32_e64 s[2:3], 0, v18
	v_not_b32_e32 v18, v19
	v_or_b32_e32 v19, 0x80000000, v19
	v_cndmask_b32_e64 v18, v19, v18, s[0:1]
	v_and_b32_e32 v18, 0xffffff00, v18
	v_or_b32_e32 v18, 0xce, v18
	v_max_u32_e32 v19, v40, v18
	v_min_u32_e32 v18, v40, v18
	v_cndmask_b32_e64 v16, v39, v16, s[2:3]
	v_max_u32_e32 v39, v20, v18
	v_min_u32_e32 v18, v20, v18
	v_max_u32_e32 v20, v41, v18
	v_min_u32_e32 v18, v41, v18
	v_max_u32_e32 v40, v21, v18
	v_min_u32_e32 v18, v21, v18
	v_max_u32_e32 v21, v22, v18
	v_min_u32_e32 v18, v22, v18
	v_max_u32_e32 v22, v23, v18
	v_min_u32_e32 v18, v23, v18
	v_max_u32_e32 v23, v28, v18
	v_min_u32_e32 v18, v28, v18
	v_max_u32_e32 v28, v30, v18
	v_min_u32_e32 v18, v30, v18
	v_max_u32_e32 v30, v31, v18
	v_min_u32_e32 v18, v31, v18
	v_max_u32_e32 v31, v32, v18
	v_min_u32_e32 v18, v32, v18
	v_max_u32_e32 v32, v33, v18
	v_min_u32_e32 v18, v33, v18
	v_max_u32_e32 v33, v34, v18
	v_min_u32_e32 v18, v34, v18
	v_and_b32_e32 v16, 0xffffff00, v16
	v_max_u32_e32 v34, v35, v18
	v_min_u32_e32 v18, v35, v18
	v_or_b32_e32 v16, 0xcd, v16
	v_max_u32_e32 v35, v36, v18
	v_min_u32_e32 v18, v36, v18
	v_max_u32_e32 v36, v37, v18
	v_min_u32_e32 v18, v37, v18
	v_max_u32_e32 v37, v19, v16
	v_min_u32_e32 v16, v19, v16
	v_max_u32_e32 v19, v39, v16
	v_min_u32_e32 v16, v39, v16
	v_max_u32_e32 v39, v20, v16
	v_min_u32_e32 v16, v20, v16
	v_max_u32_e32 v20, v40, v16
	v_min_u32_e32 v16, v40, v16
	v_max_u32_e32 v40, v21, v16
	v_min_u32_e32 v16, v21, v16
	v_max_u32_e32 v21, v22, v16
	v_min_u32_e32 v16, v22, v16
	v_max_u32_e32 v22, v23, v16
	v_min_u32_e32 v16, v23, v16
	v_max_u32_e32 v23, v28, v16
	v_min_u32_e32 v16, v28, v16
	v_max_u32_e32 v28, v30, v16
	v_min_u32_e32 v16, v30, v16
	v_max_u32_e32 v30, v31, v16
	v_min_u32_e32 v16, v31, v16
	v_max_u32_e32 v31, v32, v16
	v_min_u32_e32 v16, v32, v16
	v_max_u32_e32 v32, v33, v16
	v_min_u32_e32 v16, v33, v16
	v_max_u32_e32 v33, v34, v16
	v_min_u32_e32 v16, v34, v16
	v_max_u32_e32 v34, v35, v16
	v_min_u32_e32 v16, v35, v16
	v_max_u32_e32 v35, v36, v16
	v_min_u32_e32 v16, v36, v16
	v_min_u32_e32 v36, v37, v47
	v_max3_u32 v16, v38, v18, v16
	v_max_u32_e32 v18, v37, v47
	v_max_u32_e32 v37, v19, v36
	v_min_u32_e32 v19, v19, v36
	v_max_u32_e32 v36, v39, v19
	v_min_u32_e32 v19, v39, v19
	v_max_u32_e32 v38, v20, v19
	v_min_u32_e32 v19, v20, v19
	v_max_u32_e32 v20, v40, v19
	v_min_u32_e32 v19, v40, v19
	v_max_u32_e32 v39, v21, v19
	v_min_u32_e32 v19, v21, v19
	v_max_u32_e32 v21, v22, v19
	v_min_u32_e32 v19, v22, v19
	v_max_u32_e32 v22, v23, v19
	v_min_u32_e32 v19, v23, v19
	v_max_u32_e32 v23, v28, v19
	v_min_u32_e32 v19, v28, v19
	v_max_u32_e32 v28, v30, v19
	v_min_u32_e32 v19, v30, v19
	v_max_u32_e32 v30, v31, v19
	v_min_u32_e32 v19, v31, v19
	v_max_u32_e32 v31, v32, v19
	v_min_u32_e32 v19, v32, v19
	v_max_u32_e32 v32, v33, v19
	v_min_u32_e32 v19, v33, v19
	v_max_u32_e32 v33, v34, v19
	v_min_u32_e32 v19, v34, v19
	v_max_u32_e32 v34, v35, v19
	v_min_u32_e32 v19, v35, v19
	v_not_b32_e32 v35, v17
	v_or_b32_e32 v17, 0x80000000, v17
	v_cndmask_b32_e32 v17, v17, v35, vcc
	v_and_b32_e32 v17, 0xffffff00, v17
	v_or_b32_e32 v17, 0xbf, v17
	v_max_u32_e32 v35, v18, v17
	v_min_u32_e32 v17, v18, v17
	v_max_u32_e32 v18, v37, v17
	v_min_u32_e32 v17, v37, v17
	v_max_u32_e32 v37, v36, v17
	v_min_u32_e32 v17, v36, v17
	v_max_u32_e32 v36, v38, v17
	v_min_u32_e32 v17, v38, v17
	v_max_u32_e32 v38, v20, v17
	v_min_u32_e32 v17, v20, v17
	v_max_u32_e32 v20, v39, v17
	v_min_u32_e32 v17, v39, v17
	v_max_u32_e32 v39, v21, v17
	v_min_u32_e32 v17, v21, v17
	v_max_u32_e32 v21, v22, v17
	v_min_u32_e32 v17, v22, v17
	v_max_u32_e32 v22, v23, v17
	v_min_u32_e32 v17, v23, v17
	v_max_u32_e32 v23, v28, v17
	v_min_u32_e32 v17, v28, v17
	v_max_u32_e32 v28, v30, v17
	v_min_u32_e32 v17, v30, v17
	v_max_u32_e32 v30, v31, v17
	v_min_u32_e32 v17, v31, v17
	v_max_u32_e32 v31, v32, v17
	v_min_u32_e32 v17, v32, v17
	v_max_u32_e32 v32, v33, v17
	v_min_u32_e32 v17, v33, v17
	v_max_u32_e32 v33, v34, v17
	v_min_u32_e32 v17, v34, v17
	v_pk_add_f32 v[6:7], v[6:7], v[12:13] op_sel_hi:[1,0]
	v_max3_u32 v16, v16, v19, v17
	v_not_b32_e32 v17, v6
	v_or_b32_e32 v19, 0x80000000, v6
	v_cmp_gt_i32_e64 s[0:1], 0, v6
	v_cmp_gt_i32_e32 vcc, 0, v7
	s_nop 0
	v_cndmask_b32_e64 v6, v19, v17, s[0:1]
	v_not_b32_e32 v17, v7
	v_or_b32_e32 v7, 0x80000000, v7
	v_cndmask_b32_e32 v7, v7, v17, vcc
	v_and_b32_e32 v7, 0xffffff00, v7
	v_or_b32_e32 v7, 0xbe, v7
	v_max_u32_e32 v17, v35, v7
	v_min_u32_e32 v7, v35, v7
	v_max_u32_e32 v19, v18, v7
	v_min_u32_e32 v7, v18, v7
	v_max_u32_e32 v18, v37, v7
	v_min_u32_e32 v7, v37, v7
	v_max_u32_e32 v34, v36, v7
	v_min_u32_e32 v7, v36, v7
	v_max_u32_e32 v35, v38, v7
	v_min_u32_e32 v7, v38, v7
	v_max_u32_e32 v36, v20, v7
	v_min_u32_e32 v7, v20, v7
	v_max_u32_e32 v20, v39, v7
	v_min_u32_e32 v7, v39, v7
	v_max_u32_e32 v37, v21, v7
	v_min_u32_e32 v7, v21, v7
	v_max_u32_e32 v21, v22, v7
	v_min_u32_e32 v7, v22, v7
	v_max_u32_e32 v22, v23, v7
	v_min_u32_e32 v7, v23, v7
	v_max_u32_e32 v23, v28, v7
	v_min_u32_e32 v7, v28, v7
	v_max_u32_e32 v28, v30, v7
	v_min_u32_e32 v7, v30, v7
	v_and_b32_e32 v6, 0xffffff00, v6
	v_max_u32_e32 v30, v31, v7
	v_min_u32_e32 v7, v31, v7
	v_or_b32_e32 v6, 0xbd, v6
	v_max_u32_e32 v31, v32, v7
	v_min_u32_e32 v7, v32, v7
	v_max_u32_e32 v32, v33, v7
	v_min_u32_e32 v7, v33, v7
	v_max_u32_e32 v33, v17, v6
	v_min_u32_e32 v6, v17, v6
	v_max_u32_e32 v17, v19, v6
	v_min_u32_e32 v6, v19, v6
	v_max_u32_e32 v19, v18, v6
	v_min_u32_e32 v6, v18, v6
	v_max_u32_e32 v18, v34, v6
	v_min_u32_e32 v6, v34, v6
	v_max_u32_e32 v34, v35, v6
	v_min_u32_e32 v6, v35, v6
	v_max_u32_e32 v35, v36, v6
	v_min_u32_e32 v6, v36, v6
	v_max_u32_e32 v36, v20, v6
	v_min_u32_e32 v6, v20, v6
	v_max_u32_e32 v20, v37, v6
	v_min_u32_e32 v6, v37, v6
	v_max_u32_e32 v37, v21, v6
	v_min_u32_e32 v6, v21, v6
	v_max_u32_e32 v21, v22, v6
	v_min_u32_e32 v6, v22, v6
	v_max_u32_e32 v22, v23, v6
	v_min_u32_e32 v6, v23, v6
	v_max_u32_e32 v23, v28, v6
	v_min_u32_e32 v6, v28, v6
	v_max_u32_e32 v28, v30, v6
	v_min_u32_e32 v6, v30, v6
	v_max_u32_e32 v30, v31, v6
	v_min_u32_e32 v6, v31, v6
	v_max_u32_e32 v31, v32, v6
	v_min_u32_e32 v6, v32, v6
	v_max3_u32 v16, v16, v7, v6
	v_pk_add_f32 v[6:7], v[4:5], v[12:13] op_sel:[0,1]
	s_nop 0
	v_not_b32_e32 v12, v6
	v_or_b32_e32 v13, 0x80000000, v6
	v_cmp_gt_i32_e64 s[0:1], 0, v6
	v_cmp_gt_i32_e32 vcc, 0, v7
	s_nop 0
	v_cndmask_b32_e64 v6, v13, v12, s[0:1]
	v_and_b32_e32 v6, 0xffffff00, v6
	v_or_b32_e32 v6, 0xaf, v6
	v_max_u32_e32 v12, v33, v6
	v_min_u32_e32 v6, v33, v6
	v_max_u32_e32 v13, v17, v6
	v_min_u32_e32 v6, v17, v6
	v_max_u32_e32 v17, v19, v6
	v_min_u32_e32 v6, v19, v6
	v_max_u32_e32 v19, v18, v6
	v_min_u32_e32 v6, v18, v6
	v_max_u32_e32 v18, v34, v6
	v_min_u32_e32 v6, v34, v6
	v_max_u32_e32 v32, v35, v6
	v_min_u32_e32 v6, v35, v6
	v_max_u32_e32 v33, v36, v6
	v_min_u32_e32 v6, v36, v6
	v_max_u32_e32 v34, v20, v6
	v_min_u32_e32 v6, v20, v6
	v_max_u32_e32 v20, v37, v6
	v_min_u32_e32 v6, v37, v6
	v_max_u32_e32 v35, v21, v6
	v_min_u32_e32 v6, v21, v6
	v_max_u32_e32 v21, v22, v6
	v_min_u32_e32 v6, v22, v6
	v_max_u32_e32 v22, v23, v6
	v_min_u32_e32 v6, v23, v6
	v_max_u32_e32 v23, v28, v6
	v_min_u32_e32 v6, v28, v6
	v_max_u32_e32 v28, v30, v6
	v_min_u32_e32 v6, v30, v6
	v_max_u32_e32 v30, v31, v6
	v_min_u32_e32 v6, v31, v6
	v_not_b32_e32 v31, v7
	v_or_b32_e32 v7, 0x80000000, v7
	v_cndmask_b32_e32 v7, v7, v31, vcc
	v_and_b32_e32 v7, 0xffffff00, v7
	v_or_b32_e32 v7, 0xae, v7
	v_max_u32_e32 v31, v12, v7
	v_min_u32_e32 v7, v12, v7
	v_max_u32_e32 v12, v13, v7
	v_min_u32_e32 v7, v13, v7
	v_max_u32_e32 v13, v17, v7
	v_min_u32_e32 v7, v17, v7
	v_max_u32_e32 v17, v19, v7
	v_min_u32_e32 v7, v19, v7
	v_max_u32_e32 v19, v18, v7
	v_min_u32_e32 v7, v18, v7
	v_max_u32_e32 v18, v32, v7
	v_min_u32_e32 v7, v32, v7
	v_max_u32_e32 v32, v33, v7
	v_min_u32_e32 v7, v33, v7
	v_max_u32_e32 v33, v34, v7
	v_min_u32_e32 v7, v34, v7
	v_max_u32_e32 v34, v20, v7
	v_min_u32_e32 v7, v20, v7
	v_max_u32_e32 v20, v35, v7
	v_min_u32_e32 v7, v35, v7
	v_max_u32_e32 v35, v21, v7
	v_min_u32_e32 v7, v21, v7
	v_max_u32_e32 v21, v22, v7
	v_min_u32_e32 v7, v22, v7
	v_max_u32_e32 v22, v23, v7
	v_min_u32_e32 v7, v23, v7
	v_max_u32_e32 v23, v28, v7
	v_min_u32_e32 v7, v28, v7
	v_max_u32_e32 v28, v30, v7
	v_min_u32_e32 v7, v30, v7
	v_max3_u32 v16, v16, v6, v7
	v_pk_add_f32 v[6:7], v[4:5], v[14:15] op_sel_hi:[1,0]
	s_nop 0
	v_not_b32_e32 v14, v6
	v_or_b32_e32 v30, 0x80000000, v6
	v_cmp_gt_i32_e64 s[0:1], 0, v6
	v_cmp_gt_i32_e32 vcc, 0, v7
	s_nop 0
	v_cndmask_b32_e64 v6, v30, v14, s[0:1]
	v_and_b32_e32 v6, 0xffffff00, v6
	v_or_b32_e32 v6, 0x9f, v6
	v_max_u32_e32 v14, v31, v6
	v_min_u32_e32 v6, v31, v6
	v_max_u32_e32 v30, v12, v6
	v_min_u32_e32 v6, v12, v6
	v_max_u32_e32 v12, v13, v6
	v_min_u32_e32 v6, v13, v6
	v_max_u32_e32 v13, v17, v6
	v_min_u32_e32 v6, v17, v6
	v_max_u32_e32 v17, v19, v6
	v_min_u32_e32 v6, v19, v6
	v_max_u32_e32 v19, v18, v6
	v_min_u32_e32 v6, v18, v6
	v_max_u32_e32 v18, v32, v6
	v_min_u32_e32 v6, v32, v6
	v_max_u32_e32 v31, v33, v6
	v_min_u32_e32 v6, v33, v6
	v_max_u32_e32 v32, v34, v6
	v_min_u32_e32 v6, v34, v6
	v_max_u32_e32 v33, v20, v6
	v_min_u32_e32 v6, v20, v6
	v_max_u32_e32 v20, v35, v6
	v_min_u32_e32 v6, v35, v6
	v_max_u32_e32 v34, v21, v6
	v_min_u32_e32 v6, v21, v6
	v_max_u32_e32 v21, v22, v6
	v_min_u32_e32 v6, v22, v6
	v_max_u32_e32 v22, v23, v6
	v_min_u32_e32 v6, v23, v6
	v_max_u32_e32 v23, v28, v6
	v_min_u32_e32 v6, v28, v6
	v_not_b32_e32 v28, v7
	v_or_b32_e32 v7, 0x80000000, v7
	v_cndmask_b32_e32 v7, v7, v28, vcc
	v_and_b32_e32 v7, 0xffffff00, v7
	v_or_b32_e32 v7, 0x9e, v7
	v_max_u32_e32 v28, v14, v7
	v_min_u32_e32 v7, v14, v7
	v_max_u32_e32 v14, v30, v7
	v_min_u32_e32 v7, v30, v7
	v_max_u32_e32 v30, v12, v7
	v_min_u32_e32 v7, v12, v7
	v_max_u32_e32 v12, v13, v7
	v_min_u32_e32 v7, v13, v7
	v_max_u32_e32 v13, v17, v7
	v_min_u32_e32 v7, v17, v7
	v_max_u32_e32 v17, v19, v7
	v_min_u32_e32 v7, v19, v7
	v_max_u32_e32 v19, v18, v7
	v_min_u32_e32 v7, v18, v7
	v_max_u32_e32 v18, v31, v7
	v_min_u32_e32 v7, v31, v7
	v_max_u32_e32 v31, v32, v7
	v_min_u32_e32 v7, v32, v7
	v_max_u32_e32 v32, v33, v7
	v_min_u32_e32 v7, v33, v7
	v_max_u32_e32 v33, v20, v7
	v_min_u32_e32 v7, v20, v7
	v_max_u32_e32 v20, v34, v7
	v_min_u32_e32 v7, v34, v7
	v_max_u32_e32 v34, v21, v7
	v_min_u32_e32 v7, v21, v7
	v_max_u32_e32 v21, v22, v7
	v_min_u32_e32 v7, v22, v7
	v_max_u32_e32 v22, v23, v7
	v_min_u32_e32 v7, v23, v7
	v_max3_u32 v16, v16, v6, v7
	v_mov_b32_e32 v6, v15
	v_pk_add_f32 v[6:7], v[4:5], v[6:7] op_sel_hi:[1,0]
	s_nop 0
	v_not_b32_e32 v15, v6
	v_or_b32_e32 v23, 0x80000000, v6
	v_cmp_gt_i32_e64 s[0:1], 0, v6
	v_cmp_gt_i32_e32 vcc, 0, v7
	s_nop 0
	v_cndmask_b32_e64 v6, v23, v15, s[0:1]
	v_and_b32_e32 v6, 0xffffff00, v6
	v_or_b32_e32 v6, 0x8f, v6
	v_max_u32_e32 v15, v28, v6
	v_min_u32_e32 v6, v28, v6
	v_max_u32_e32 v23, v14, v6
	v_min_u32_e32 v6, v14, v6
	v_max_u32_e32 v14, v30, v6
	v_min_u32_e32 v6, v30, v6
	v_max_u32_e32 v28, v12, v6
	v_min_u32_e32 v6, v12, v6
	v_max_u32_e32 v12, v13, v6
	v_min_u32_e32 v6, v13, v6
	v_max_u32_e32 v13, v17, v6
	v_min_u32_e32 v6, v17, v6
	v_max_u32_e32 v17, v19, v6
	v_min_u32_e32 v6, v19, v6
	v_max_u32_e32 v19, v18, v6
	v_min_u32_e32 v6, v18, v6
	v_max_u32_e32 v18, v31, v6
	v_min_u32_e32 v6, v31, v6
	v_max_u32_e32 v30, v32, v6
	v_min_u32_e32 v6, v32, v6
	v_max_u32_e32 v31, v33, v6
	v_min_u32_e32 v6, v33, v6
	v_max_u32_e32 v32, v20, v6
	v_min_u32_e32 v6, v20, v6
	v_max_u32_e32 v20, v34, v6
	v_min_u32_e32 v6, v34, v6
	v_max_u32_e32 v33, v21, v6
	v_min_u32_e32 v6, v21, v6
	v_max_u32_e32 v21, v22, v6
	v_min_u32_e32 v6, v22, v6
	v_not_b32_e32 v22, v7
	v_or_b32_e32 v7, 0x80000000, v7
	v_cndmask_b32_e32 v7, v7, v22, vcc
	v_and_b32_e32 v7, 0xffffff00, v7
	v_or_b32_e32 v7, 0x8e, v7
	v_max_u32_e32 v22, v15, v7
	v_min_u32_e32 v7, v15, v7
	v_max_u32_e32 v15, v23, v7
	v_min_u32_e32 v7, v23, v7
	v_max_u32_e32 v23, v14, v7
	v_min_u32_e32 v7, v14, v7
	v_max_u32_e32 v14, v28, v7
	v_min_u32_e32 v7, v28, v7
	v_max_u32_e32 v28, v12, v7
	v_min_u32_e32 v7, v12, v7
	v_max_u32_e32 v34, v13, v7
	v_min_u32_e32 v7, v13, v7
	v_max_u32_e32 v35, v17, v7
	v_min_u32_e32 v7, v17, v7
	v_max_u32_e32 v17, v19, v7
	v_min_u32_e32 v7, v19, v7
	v_max_u32_e32 v19, v18, v7
	v_min_u32_e32 v7, v18, v7
	v_max_u32_e32 v18, v30, v7
	v_min_u32_e32 v7, v30, v7
	v_max_u32_e32 v30, v31, v7
	v_min_u32_e32 v7, v31, v7
	v_max_u32_e32 v31, v32, v7
	v_min_u32_e32 v7, v32, v7
	v_max_u32_e32 v32, v20, v7
	v_min_u32_e32 v7, v20, v7
	v_max_u32_e32 v20, v33, v7
	v_min_u32_e32 v7, v33, v7
	v_max_u32_e32 v33, v21, v7
	v_min_u32_e32 v7, v21, v7
	v_max3_u32 v16, v16, v6, v7
	v_pk_mov_b32 v[6:7], v[8:9], v[4:5] op_sel:[1,0]
	v_mov_b32_e32 v12, v4
	v_mov_b32_e32 v13, v8
	v_pk_add_f32 v[6:7], v[6:7], v[12:13]
	s_nop 0
	v_not_b32_e32 v8, v7
	v_or_b32_e32 v9, 0x80000000, v7
	v_cmp_gt_i32_e64 s[0:1], 0, v7
	v_cmp_gt_i32_e32 vcc, 0, v6
	s_nop 0
	v_cndmask_b32_e64 v7, v9, v8, s[0:1]
	v_and_b32_e32 v7, 0xffffff00, v7
	v_or_b32_e32 v7, 0x7f, v7
	v_max_u32_e32 v8, v22, v7
	v_min_u32_e32 v7, v22, v7
	v_max_u32_e32 v9, v15, v7
	v_min_u32_e32 v7, v15, v7
	v_max_u32_e32 v12, v23, v7
	v_min_u32_e32 v7, v23, v7
	v_max_u32_e32 v13, v14, v7
	v_min_u32_e32 v7, v14, v7
	v_max_u32_e32 v14, v28, v7
	v_min_u32_e32 v7, v28, v7
	v_max_u32_e32 v15, v34, v7
	v_min_u32_e32 v7, v34, v7
	v_max_u32_e32 v21, v35, v7
	v_min_u32_e32 v7, v35, v7
	v_max_u32_e32 v22, v17, v7
	v_min_u32_e32 v7, v17, v7
	v_max_u32_e32 v17, v19, v7
	v_min_u32_e32 v7, v19, v7
	v_max_u32_e32 v19, v18, v7
	v_min_u32_e32 v7, v18, v7
	v_max_u32_e32 v18, v30, v7
	v_min_u32_e32 v7, v30, v7
	v_max_u32_e32 v23, v31, v7
	v_min_u32_e32 v7, v31, v7
	v_not_b32_e32 v31, v6
	v_or_b32_e32 v6, 0x80000000, v6
	v_cndmask_b32_e32 v6, v6, v31, vcc
	v_and_b32_e32 v6, 0xffffff00, v6
	v_or_b32_e32 v6, 0x6f, v6
	v_max_u32_e32 v28, v32, v7
	v_min_u32_e32 v7, v32, v7
	v_max_u32_e32 v31, v8, v6
	v_min_u32_e32 v6, v8, v6
	v_max_u32_e32 v30, v20, v7
	v_min_u32_e32 v7, v20, v7
	v_max_u32_e32 v32, v9, v6
	v_min_u32_e32 v6, v9, v6
	v_max_u32_e32 v20, v33, v7
	v_min_u32_e32 v7, v33, v7
	v_max_u32_e32 v33, v12, v6
	v_min_u32_e32 v6, v12, v6
	v_max_u32_e32 v12, v13, v6
	v_min_u32_e32 v6, v13, v6
	v_max_u32_e32 v13, v14, v6
	v_min_u32_e32 v6, v14, v6
	v_max_u32_e32 v14, v15, v6
	v_min_u32_e32 v6, v15, v6
	v_max_u32_e32 v15, v21, v6
	v_min_u32_e32 v6, v21, v6
	v_max_u32_e32 v21, v22, v6
	v_min_u32_e32 v6, v22, v6
	v_max_u32_e32 v22, v17, v6
	v_min_u32_e32 v6, v17, v6
	v_max_u32_e32 v17, v19, v6
	v_min_u32_e32 v6, v19, v6
	v_max_u32_e32 v19, v18, v6
	v_min_u32_e32 v6, v18, v6
	v_max_u32_e32 v18, v23, v6
	v_min_u32_e32 v6, v23, v6
	v_max_u32_e32 v23, v28, v6
	v_min_u32_e32 v6, v28, v6
	v_max_u32_e32 v28, v30, v6
	v_min_u32_e32 v6, v30, v6
	v_max_u32_e32 v30, v20, v6
	v_min_u32_e32 v6, v20, v6
	v_max3_u32 v16, v16, v7, v6
	v_pk_mov_b32 v[6:7], v[10:11], v[4:5] op_sel:[1,0]
	v_mov_b32_e32 v8, v4
	v_mov_b32_e32 v9, v10
	v_pk_add_f32 v[6:7], v[6:7], v[8:9]
	s_nop 0
	v_not_b32_e32 v8, v7
	v_or_b32_e32 v9, 0x80000000, v7
	v_cmp_gt_i32_e64 s[0:1], 0, v7
	v_cmp_gt_i32_e32 vcc, 0, v6
	s_nop 0
	v_cndmask_b32_e64 v7, v9, v8, s[0:1]
	v_and_b32_e32 v7, 0xffffff00, v7
	v_or_b32_e32 v7, 0x5f, v7
	v_max_u32_e32 v8, v31, v7
	v_min_u32_e32 v7, v31, v7
	v_max_u32_e32 v9, v32, v7
	v_min_u32_e32 v7, v32, v7
	v_max_u32_e32 v10, v33, v7
	v_min_u32_e32 v7, v33, v7
	v_max_u32_e32 v11, v12, v7
	v_min_u32_e32 v7, v12, v7
	v_max_u32_e32 v12, v13, v7
	v_min_u32_e32 v7, v13, v7
	v_max_u32_e32 v13, v14, v7
	v_min_u32_e32 v7, v14, v7
	v_max_u32_e32 v14, v15, v7
	v_min_u32_e32 v7, v15, v7
	v_max_u32_e32 v15, v21, v7
	v_min_u32_e32 v7, v21, v7
	v_max_u32_e32 v20, v22, v7
	v_min_u32_e32 v7, v22, v7
	v_max_u32_e32 v21, v17, v7
	v_min_u32_e32 v7, v17, v7
	v_max_u32_e32 v17, v19, v7
	v_min_u32_e32 v7, v19, v7
	v_max_u32_e32 v19, v18, v7
	v_min_u32_e32 v7, v18, v7
	v_max_u32_e32 v18, v23, v7
	v_min_u32_e32 v7, v23, v7
	v_max_u32_e32 v22, v28, v7
	v_min_u32_e32 v7, v28, v7
	v_not_b32_e32 v28, v6
	v_or_b32_e32 v6, 0x80000000, v6
	v_cndmask_b32_e32 v6, v6, v28, vcc
	v_and_b32_e32 v6, 0xffffff00, v6
	v_or_b32_e32 v6, 0x4f, v6
	v_max_u32_e32 v28, v8, v6
	v_min_u32_e32 v6, v8, v6
	v_max_u32_e32 v23, v30, v7
	v_min_u32_e32 v7, v30, v7
	v_max_u32_e32 v30, v9, v6
	v_min_u32_e32 v6, v9, v6
	v_max_u32_e32 v31, v10, v6
	v_min_u32_e32 v6, v10, v6
	v_max_u32_e32 v10, v11, v6
	v_min_u32_e32 v6, v11, v6
	v_max_u32_e32 v11, v12, v6
	v_min_u32_e32 v6, v12, v6
	v_max_u32_e32 v12, v13, v6
	v_min_u32_e32 v6, v13, v6
	v_max_u32_e32 v13, v14, v6
	v_min_u32_e32 v6, v14, v6
	v_max_u32_e32 v14, v15, v6
	v_min_u32_e32 v6, v15, v6
	v_max_u32_e32 v15, v20, v6
	v_min_u32_e32 v6, v20, v6
	v_max_u32_e32 v20, v21, v6
	v_min_u32_e32 v6, v21, v6
	v_max_u32_e32 v21, v17, v6
	v_min_u32_e32 v6, v17, v6
	v_max_u32_e32 v17, v19, v6
	v_min_u32_e32 v6, v19, v6
	v_max_u32_e32 v19, v18, v6
	v_min_u32_e32 v6, v18, v6
	v_max_u32_e32 v18, v22, v6
	v_min_u32_e32 v6, v22, v6
	v_max_u32_e32 v22, v23, v6
	v_min_u32_e32 v6, v23, v6
	v_max3_u32 v16, v16, v7, v6
	v_pk_mov_b32 v[6:7], v[0:1], v[4:5] op_sel:[1,0]
	v_mov_b32_e32 v8, v4
	v_mov_b32_e32 v9, v0
	v_pk_add_f32 v[0:1], v[6:7], v[8:9]
	s_nop 0
	v_not_b32_e32 v6, v1
	v_or_b32_e32 v7, 0x80000000, v1
	v_cmp_gt_i32_e64 s[0:1], 0, v1
	v_cmp_gt_i32_e32 vcc, 0, v0
	s_nop 0
	v_cndmask_b32_e64 v1, v7, v6, s[0:1]
	v_and_or_b32 v1, v1, s5, 63
	v_max_u32_e32 v6, v28, v1
	v_min_u32_e32 v1, v28, v1
	v_max_u32_e32 v7, v30, v1
	v_min_u32_e32 v1, v30, v1
	v_max_u32_e32 v8, v31, v1
	v_min_u32_e32 v1, v31, v1
	v_max_u32_e32 v9, v10, v1
	v_min_u32_e32 v1, v10, v1
	v_max_u32_e32 v10, v11, v1
	v_min_u32_e32 v1, v11, v1
	v_max_u32_e32 v11, v12, v1
	v_min_u32_e32 v1, v12, v1
	v_max_u32_e32 v12, v13, v1
	v_min_u32_e32 v1, v13, v1
	v_max_u32_e32 v13, v14, v1
	v_min_u32_e32 v1, v14, v1
	v_max_u32_e32 v14, v15, v1
	v_min_u32_e32 v1, v15, v1
	v_max_u32_e32 v15, v20, v1
	v_min_u32_e32 v1, v20, v1
	v_max_u32_e32 v20, v21, v1
	v_min_u32_e32 v1, v21, v1
	v_max_u32_e32 v21, v17, v1
	v_min_u32_e32 v1, v17, v1
	v_max_u32_e32 v17, v19, v1
	v_min_u32_e32 v1, v19, v1
	v_max_u32_e32 v19, v18, v1
	v_min_u32_e32 v1, v18, v1
	v_max_u32_e32 v18, v22, v1
	v_min_u32_e32 v1, v22, v1
	v_not_b32_e32 v22, v0
	v_or_b32_e32 v0, 0x80000000, v0
	v_cndmask_b32_e32 v0, v0, v22, vcc
	v_and_or_b32 v0, v0, s5, 47
	v_max_u32_e32 v22, v6, v0
	v_min_u32_e32 v0, v6, v0
	v_max_u32_e32 v6, v7, v0
	v_min_u32_e32 v0, v7, v0
	v_max_u32_e32 v7, v8, v0
	v_min_u32_e32 v0, v8, v0
	v_max_u32_e32 v8, v9, v0
	v_min_u32_e32 v0, v9, v0
	v_max_u32_e32 v9, v10, v0
	v_min_u32_e32 v0, v10, v0
	v_max_u32_e32 v10, v11, v0
	v_min_u32_e32 v0, v11, v0
	v_max_u32_e32 v11, v12, v0
	v_min_u32_e32 v0, v12, v0
	v_max_u32_e32 v12, v13, v0
	v_min_u32_e32 v0, v13, v0
	v_max_u32_e32 v13, v14, v0
	v_min_u32_e32 v0, v14, v0
	v_max_u32_e32 v14, v15, v0
	v_min_u32_e32 v0, v15, v0
	v_max_u32_e32 v15, v20, v0
	v_min_u32_e32 v0, v20, v0
	v_max_u32_e32 v20, v21, v0
	v_min_u32_e32 v0, v21, v0
	v_max_u32_e32 v21, v17, v0
	v_min_u32_e32 v0, v17, v0
	v_max_u32_e32 v17, v19, v0
	v_min_u32_e32 v0, v19, v0
	v_max_u32_e32 v19, v18, v0
	v_min_u32_e32 v0, v18, v0
	v_max3_u32 v28, v16, v1, v0
	v_pk_mov_b32 v[0:1], v[2:3], v[4:5] op_sel:[1,0]
	v_mov_b32_e32 v5, v2
	v_pk_add_f32 v[0:1], v[0:1], v[4:5]
	s_nop 0
	v_not_b32_e32 v2, v1
	v_or_b32_e32 v3, 0x80000000, v1
	v_cmp_gt_i32_e64 s[0:1], 0, v1
	v_cmp_gt_i32_e32 vcc, 0, v0
	s_nop 0
	v_cndmask_b32_e64 v1, v3, v2, s[0:1]
	v_and_or_b32 v1, v1, s5, 31
	v_max_u32_e32 v2, v22, v1
	v_min_u32_e32 v1, v22, v1
	v_max_u32_e32 v3, v6, v1
	v_min_u32_e32 v1, v6, v1
	v_max_u32_e32 v4, v7, v1
	v_min_u32_e32 v1, v7, v1
	v_max_u32_e32 v5, v8, v1
	v_min_u32_e32 v1, v8, v1
	v_max_u32_e32 v6, v9, v1
	v_min_u32_e32 v1, v9, v1
	v_max_u32_e32 v7, v10, v1
	v_min_u32_e32 v1, v10, v1
	v_max_u32_e32 v8, v11, v1
	v_min_u32_e32 v1, v11, v1
	v_max_u32_e32 v9, v12, v1
	v_min_u32_e32 v1, v12, v1
	v_max_u32_e32 v10, v13, v1
	v_min_u32_e32 v1, v13, v1
	v_not_b32_e32 v13, v0
	v_or_b32_e32 v0, 0x80000000, v0
	v_cndmask_b32_e32 v0, v0, v13, vcc
	v_and_or_b32 v0, v0, s5, 15
	v_max_u32_e32 v44, v2, v0
	v_min_u32_e32 v0, v2, v0
	v_max_u32_e32 v38, v3, v0
	v_min_u32_e32 v0, v3, v0
	v_max_u32_e32 v36, v4, v0
	v_min_u32_e32 v0, v4, v0
	v_max_u32_e32 v34, v5, v0
	v_min_u32_e32 v0, v5, v0
	v_max_u32_e32 v32, v6, v0
	v_min_u32_e32 v0, v6, v0
	v_max_u32_e32 v11, v14, v1
	v_min_u32_e32 v1, v14, v1
	v_max_u32_e32 v30, v7, v0
	v_min_u32_e32 v0, v7, v0
	v_max_u32_e32 v12, v15, v1
	v_min_u32_e32 v1, v15, v1
	v_max_u32_e32 v22, v8, v0
	v_min_u32_e32 v0, v8, v0
	v_max_u32_e32 v40, v20, v1
	v_min_u32_e32 v1, v20, v1
	v_max_u32_e32 v20, v9, v0
	v_min_u32_e32 v0, v9, v0
	v_max_u32_e32 v18, v10, v0
	v_min_u32_e32 v0, v10, v0
	v_max_u32_e32 v16, v11, v0
	v_min_u32_e32 v0, v11, v0
	v_max_u32_e32 v14, v12, v0
	v_min_u32_e32 v0, v12, v0
	v_max_u32_e32 v41, v21, v1
	v_min_u32_e32 v1, v21, v1
	v_max_u32_e32 v12, v40, v0
	v_min_u32_e32 v0, v40, v0
	v_max_u32_e32 v42, v17, v1
	v_min_u32_e32 v1, v17, v1
	v_max_u32_e32 v10, v41, v0
	v_min_u32_e32 v0, v41, v0
	v_max_u32_e32 v43, v19, v1
	v_max_u32_e32 v8, v42, v0
	v_min_u32_e32 v0, v42, v0
	v_min_u32_e32 v1, v19, v1
	v_max_u32_e32 v6, v43, v0
	v_min_u32_e32 v0, v43, v0
	v_max3_u32 v4, v28, v1, v0
	v_lshlrev_b32_e32 v66, 2, v130
	s_waitcnt vmcnt(0)
	ds_write_b32 v66, v156
	ds_write_b32 v66, v157 offset:1024
	ds_write_b32 v66, v158 offset:2048
	ds_write_b32 v66, v159 offset:3072
	ds_write_b32 v66, v160 offset:4096
	ds_write_b32 v66, v161 offset:5120
	ds_write_b32 v66, v162 offset:6144
	ds_write_b32 v66, v163 offset:7168
	ds_write_b32 v66, v164 offset:8192
	ds_write_b32 v66, v165 offset:9216
	ds_write_b32 v66, v166 offset:10240
	ds_write_b32 v66, v167 offset:11264
	ds_write_b32 v66, v168 offset:12288
	ds_write_b32 v66, v169 offset:13312
	ds_write_b32 v66, v170 offset:14336
	ds_write_b32 v66, v171 offset:15360
	ds_write_b32 v66, v172 offset:16384
	ds_write_b32 v66, v173 offset:17408
	ds_write_b32 v66, v174 offset:18432
	ds_write_b32 v66, v175 offset:19456
	ds_write_b32 v66, v176 offset:20480
	ds_write_b32 v66, v177 offset:21504
	ds_write_b32 v66, v178 offset:22528
	ds_write_b32 v66, v179 offset:23552
	ds_write_b32 v66, v180 offset:24576
	ds_write_b32 v66, v181 offset:25600
	ds_write_b32 v66, v182 offset:26624
	ds_write_b32 v66, v183 offset:27648
	ds_write_b32 v66, v184 offset:28672
	ds_write_b32 v66, v185 offset:29696
	ds_write_b32 v66, v186 offset:30720
	ds_write_b32 v66, v187 offset:31744
	ds_write_b32 v66, v188 offset:32768
	ds_write_b32 v66, v189 offset:33792
	ds_write_b32 v66, v190 offset:34816
	ds_write_b32 v66, v191 offset:35840
	ds_write_b32 v66, v192 offset:36864
	ds_write_b32 v66, v193 offset:37888
	ds_write_b32 v66, v194 offset:38912
	ds_write_b32 v66, v195 offset:39936
	ds_write_b32 v66, v196 offset:40960
	ds_write_b32 v66, v197 offset:41984
	ds_write_b32 v66, v198 offset:43008
	ds_write_b32 v66, v199 offset:44032
	ds_write_b32 v66, v200 offset:45056
	ds_write_b32 v66, v201 offset:46080
	ds_write_b32 v66, v202 offset:47104
	ds_write_b32 v66, v203 offset:48128
	ds_write_b32 v66, v204 offset:49152
	ds_write_b32 v66, v205 offset:50176
	ds_write_b32 v66, v206 offset:51200
	ds_write_b32 v66, v207 offset:52224
	ds_write_b32 v66, v208 offset:53248
	ds_write_b32 v66, v209 offset:54272
	ds_write_b32 v66, v210 offset:55296
	ds_write_b32 v66, v211 offset:56320
	ds_write_b32 v66, v212 offset:57344
	ds_write_b32 v66, v213 offset:58368
	ds_write_b32 v66, v214 offset:59392
	ds_write_b32 v66, v215 offset:60416
	ds_write_b32 v66, v216 offset:61440
	ds_write_b32 v66, v217 offset:62464
	ds_write_b32 v66, v218 offset:63488
	ds_write_b32 v66, v219 offset:64512
	v_not_b32_e32 v45, v44
	v_bfe_u32 v28, v45, 4, 4
	v_and_b32_e32 v45, 15, v45
	v_lshl_add_u32 v46, v28, 10, v66
	v_lshl_add_u32 v84, v45, 10, v66
	v_not_b32_e32 v45, v38
	v_bfe_u32 v28, v45, 4, 4
	v_and_b32_e32 v45, 15, v45
	v_lshl_add_u32 v47, v28, 10, v66
	v_lshl_add_u32 v85, v45, 10, v66
	v_not_b32_e32 v45, v36
	v_bfe_u32 v28, v45, 4, 4
	v_and_b32_e32 v45, 15, v45
	v_lshl_add_u32 v48, v28, 10, v66
	v_lshl_add_u32 v86, v45, 10, v66
	v_not_b32_e32 v45, v34
	v_bfe_u32 v28, v45, 4, 4
	v_and_b32_e32 v45, 15, v45
	v_lshl_add_u32 v49, v28, 10, v66
	v_lshl_add_u32 v87, v45, 10, v66
	v_not_b32_e32 v45, v32
	v_bfe_u32 v28, v45, 4, 4
	v_and_b32_e32 v45, 15, v45
	v_lshl_add_u32 v50, v28, 10, v66
	v_lshl_add_u32 v88, v45, 10, v66
	v_not_b32_e32 v45, v30
	v_bfe_u32 v28, v45, 4, 4
	v_and_b32_e32 v45, 15, v45
	v_lshl_add_u32 v51, v28, 10, v66
	v_lshl_add_u32 v89, v45, 10, v66
	v_not_b32_e32 v45, v22
	v_bfe_u32 v28, v45, 4, 4
	v_and_b32_e32 v45, 15, v45
	v_lshl_add_u32 v52, v28, 10, v66
	v_lshl_add_u32 v90, v45, 10, v66
	v_not_b32_e32 v45, v20
	v_bfe_u32 v28, v45, 4, 4
	v_and_b32_e32 v45, 15, v45
	v_lshl_add_u32 v53, v28, 10, v66
	v_lshl_add_u32 v91, v45, 10, v66
	v_not_b32_e32 v45, v18
	v_bfe_u32 v28, v45, 4, 4
	v_and_b32_e32 v45, 15, v45
	v_lshl_add_u32 v54, v28, 10, v66
	v_lshl_add_u32 v92, v45, 10, v66
	v_not_b32_e32 v45, v16
	v_bfe_u32 v28, v45, 4, 4
	v_and_b32_e32 v45, 15, v45
	v_lshl_add_u32 v55, v28, 10, v66
	v_lshl_add_u32 v93, v45, 10, v66
	v_not_b32_e32 v45, v14
	v_bfe_u32 v28, v45, 4, 4
	v_and_b32_e32 v45, 15, v45
	v_lshl_add_u32 v56, v28, 10, v66
	v_lshl_add_u32 v94, v45, 10, v66
	v_not_b32_e32 v45, v12
	v_bfe_u32 v28, v45, 4, 4
	v_and_b32_e32 v45, 15, v45
	v_lshl_add_u32 v57, v28, 10, v66
	v_lshl_add_u32 v95, v45, 10, v66
	v_not_b32_e32 v45, v10
	v_bfe_u32 v28, v45, 4, 4
	v_and_b32_e32 v45, 15, v45
	v_lshl_add_u32 v58, v28, 10, v66
	v_lshl_add_u32 v96, v45, 10, v66
	v_not_b32_e32 v45, v8
	v_bfe_u32 v28, v45, 4, 4
	v_and_b32_e32 v45, 15, v45
	v_lshl_add_u32 v59, v28, 10, v66
	v_lshl_add_u32 v97, v45, 10, v66
	v_not_b32_e32 v45, v6
	v_bfe_u32 v28, v45, 4, 4
	v_and_b32_e32 v45, 15, v45
	v_lshl_add_u32 v60, v28, 10, v66
	v_lshl_add_u32 v98, v45, 10, v66
	v_not_b32_e32 v45, v4
	v_bfe_u32 v28, v45, 4, 4
	v_and_b32_e32 v45, 15, v45
	v_lshl_add_u32 v61, v28, 10, v66
	v_lshl_add_u32 v99, v45, 10, v66
	ds_read_b32 v100, v46
	ds_read_b32 v156, v84 offset:16384
	ds_read_b32 v101, v47
	ds_read_b32 v157, v85 offset:16384
	ds_read_b32 v102, v48
	ds_read_b32 v158, v86 offset:16384
	ds_read_b32 v103, v49
	ds_read_b32 v159, v87 offset:16384
	ds_read_b32 v104, v50
	ds_read_b32 v160, v88 offset:16384
	ds_read_b32 v105, v51
	ds_read_b32 v161, v89 offset:16384
	ds_read_b32 v106, v52
	ds_read_b32 v162, v90 offset:16384
	ds_read_b32 v107, v53
	ds_read_b32 v163, v91 offset:16384
	ds_read_b32 v108, v54
	ds_read_b32 v164, v92 offset:16384
	ds_read_b32 v109, v55
	ds_read_b32 v165, v93 offset:16384
	ds_read_b32 v110, v56
	ds_read_b32 v166, v94 offset:16384
	ds_read_b32 v111, v57
	ds_read_b32 v167, v95 offset:16384
	ds_read_b32 v112, v58
	ds_read_b32 v168, v96 offset:16384
	ds_read_b32 v113, v59
	ds_read_b32 v169, v97 offset:16384
	ds_read_b32 v114, v60
	ds_read_b32 v170, v98 offset:16384
	ds_read_b32 v115, v61
	ds_read_b32 v171, v99 offset:16384
	ds_read_b32 v46, v46 offset:32768
	ds_read_b32 v84, v84 offset:49152
	ds_read_b32 v47, v47 offset:32768
	ds_read_b32 v85, v85 offset:49152
	ds_read_b32 v48, v48 offset:32768
	ds_read_b32 v86, v86 offset:49152
	ds_read_b32 v49, v49 offset:32768
	ds_read_b32 v87, v87 offset:49152
	ds_read_b32 v50, v50 offset:32768
	ds_read_b32 v88, v88 offset:49152
	ds_read_b32 v51, v51 offset:32768
	ds_read_b32 v89, v89 offset:49152
	ds_read_b32 v52, v52 offset:32768
	ds_read_b32 v90, v90 offset:49152
	ds_read_b32 v53, v53 offset:32768
	ds_read_b32 v91, v91 offset:49152
	ds_read_b32 v54, v54 offset:32768
	ds_read_b32 v92, v92 offset:49152
	ds_read_b32 v55, v55 offset:32768
	ds_read_b32 v93, v93 offset:49152
	ds_read_b32 v56, v56 offset:32768
	ds_read_b32 v94, v94 offset:49152
	ds_read_b32 v57, v57 offset:32768
	ds_read_b32 v95, v95 offset:49152
	ds_read_b32 v58, v58 offset:32768
	ds_read_b32 v96, v96 offset:49152
	ds_read_b32 v59, v59 offset:32768
	ds_read_b32 v97, v97 offset:49152
	ds_read_b32 v60, v60 offset:32768
	ds_read_b32 v98, v98 offset:49152
	ds_read_b32 v61, v61 offset:32768
	ds_read_b32 v99, v99 offset:49152
	v_lshl_add_u64 v[26:27], v[26:27], 0, s[18:19]
	v_add_co_u32_e32 v116, vcc, s27, v24
	s_nop 1
	v_addc_co_u32_e32 v117, vcc, -1, v25, vcc
	v_add_co_u32_e32 v118, vcc, s28, v24
	s_nop 1
	v_addc_co_u32_e32 v119, vcc, -1, v25, vcc
	v_lshl_add_u64 v[24:25], v[24:25], 0, s[16:17]
	v_cmp_lt_u64_e32 vcc, s[24:25], v[134:135]
	s_nop 1
	s_or_b64 s[20:21], vcc, s[20:21]
	s_waitcnt lgkmcnt(15)
	s_waitcnt lgkmcnt(0)
	v_add_f32_e32 v100, v100, v156
	v_add_f32_e32 v101, v101, v157
	v_add_f32_e32 v102, v102, v158
	v_add_f32_e32 v103, v103, v159
	v_add_f32_e32 v104, v104, v160
	v_add_f32_e32 v105, v105, v161
	v_add_f32_e32 v106, v106, v162
	v_add_f32_e32 v107, v107, v163
	v_add_f32_e32 v108, v108, v164
	v_add_f32_e32 v109, v109, v165
	v_add_f32_e32 v110, v110, v166
	v_add_f32_e32 v111, v111, v167
	v_add_f32_e32 v112, v112, v168
	v_add_f32_e32 v113, v113, v169
	v_add_f32_e32 v114, v114, v170
	v_add_f32_e32 v115, v115, v171
	v_max3_f32 v28, v100, s26, v101
	v_max3_f32 v28, v28, v102, v103
	v_max3_f32 v28, v28, v104, v105
	v_max3_f32 v28, v28, v106, v107
	v_max3_f32 v28, v28, v108, v109
	v_max3_f32 v28, v28, v110, v111
	v_max3_f32 v28, v28, v112, v113
	v_max3_f32 v28, v28, v114, v115
	v_sub_f32_e32 v156, v100, v28
	v_sub_f32_e32 v157, v101, v28
	v_sub_f32_e32 v158, v102, v28
	v_sub_f32_e32 v159, v103, v28
	v_sub_f32_e32 v160, v104, v28
	v_sub_f32_e32 v161, v105, v28
	v_sub_f32_e32 v162, v106, v28
	v_sub_f32_e32 v163, v107, v28
	v_sub_f32_e32 v164, v108, v28
	v_sub_f32_e32 v165, v109, v28
	v_sub_f32_e32 v166, v110, v28
	v_sub_f32_e32 v167, v111, v28
	v_sub_f32_e32 v168, v112, v28
	v_sub_f32_e32 v169, v113, v28
	v_sub_f32_e32 v170, v114, v28
	v_sub_f32_e32 v171, v115, v28
	v_mul_f32_e32 v156, 0x3fb8aa3b, v156
	v_mul_f32_e32 v157, 0x3fb8aa3b, v157
	v_mul_f32_e32 v158, 0x3fb8aa3b, v158
	v_mul_f32_e32 v159, 0x3fb8aa3b, v159
	v_mul_f32_e32 v160, 0x3fb8aa3b, v160
	v_mul_f32_e32 v161, 0x3fb8aa3b, v161
	v_mul_f32_e32 v162, 0x3fb8aa3b, v162
	v_mul_f32_e32 v163, 0x3fb8aa3b, v163
	v_mul_f32_e32 v164, 0x3fb8aa3b, v164
	v_mul_f32_e32 v165, 0x3fb8aa3b, v165
	v_mul_f32_e32 v166, 0x3fb8aa3b, v166
	v_mul_f32_e32 v167, 0x3fb8aa3b, v167
	v_mul_f32_e32 v168, 0x3fb8aa3b, v168
	v_mul_f32_e32 v169, 0x3fb8aa3b, v169
	v_mul_f32_e32 v170, 0x3fb8aa3b, v170
	v_mul_f32_e32 v171, 0x3fb8aa3b, v171
	v_exp_f32_e32 v156, v156
	v_exp_f32_e32 v157, v157
	v_exp_f32_e32 v158, v158
	v_exp_f32_e32 v159, v159
	v_exp_f32_e32 v160, v160
	v_exp_f32_e32 v161, v161
	v_exp_f32_e32 v162, v162
	v_exp_f32_e32 v163, v163
	v_exp_f32_e32 v164, v164
	v_exp_f32_e32 v165, v165
	v_exp_f32_e32 v166, v166
	v_exp_f32_e32 v167, v167
	v_exp_f32_e32 v168, v168
	v_exp_f32_e32 v169, v169
	v_exp_f32_e32 v170, v170
	v_exp_f32_e32 v171, v171
	s_nop 0
	v_add_f32_e32 v62, 0, v156
	v_add_f32_e32 v62, v157, v62
	v_add_f32_e32 v62, v158, v62
	v_add_f32_e32 v62, v159, v62
	v_add_f32_e32 v62, v160, v62
	v_add_f32_e32 v62, v161, v62
	v_add_f32_e32 v62, v162, v62
	v_add_f32_e32 v62, v163, v62
	v_add_f32_e32 v62, v164, v62
	v_add_f32_e32 v62, v165, v62
	v_add_f32_e32 v62, v166, v62
	v_add_f32_e32 v62, v167, v62
	v_add_f32_e32 v62, v168, v62
	v_add_f32_e32 v62, v169, v62
	v_add_f32_e32 v62, v170, v62
	v_add_f32_e32 v62, v171, v62
	v_div_scale_f32 v63, s[0:1], v62, v62, 1.0
	v_rcp_f32_e32 v64, v63
	s_nop 0
	v_fma_f32 v120, -v63, v64, 1.0
	v_fmac_f32_e32 v64, v120, v64
	v_div_scale_f32 v120, vcc, 1.0, v62, 1.0
	v_mul_f32_e32 v121, v120, v64
	v_fma_f32 v124, -v63, v121, v120
	v_fmac_f32_e32 v121, v124, v64
	v_fma_f32 v63, -v63, v121, v120
	v_div_fmas_f32 v63, v63, v64, v121
	s_nop 1
	v_div_fixup_f32 v122, v63, v62, 1.0
	s_nop 0
	v_pk_mul_f32 v[156:157], v[156:157], v[122:123] op_sel_hi:[1,0]
	v_pk_mul_f32 v[158:159], v[158:159], v[122:123] op_sel_hi:[1,0]
	v_pk_mul_f32 v[160:161], v[160:161], v[122:123] op_sel_hi:[1,0]
	v_pk_mul_f32 v[162:163], v[162:163], v[122:123] op_sel_hi:[1,0]
	v_pk_mul_f32 v[164:165], v[164:165], v[122:123] op_sel_hi:[1,0]
	v_pk_mul_f32 v[166:167], v[166:167], v[122:123] op_sel_hi:[1,0]
	v_pk_mul_f32 v[168:169], v[168:169], v[122:123] op_sel_hi:[1,0]
	v_pk_mul_f32 v[170:171], v[170:171], v[122:123] op_sel_hi:[1,0]
	global_store_dwordx4 v[118:119], v[156:159], off
	global_store_dwordx4 v[118:119], v[160:163], off offset:16
	global_store_dwordx4 v[118:119], v[164:167], off offset:32
	global_store_dwordx4 v[118:119], v[168:171], off offset:48
	v_lshl_add_u32 v46, v46, 7, v84
	v_lshl_add_u32 v47, v47, 7, v85
	v_lshl_add_u32 v48, v48, 7, v86
	v_lshl_add_u32 v49, v49, 7, v87
	v_lshl_add_u32 v50, v50, 7, v88
	v_lshl_add_u32 v51, v51, 7, v89
	v_lshl_add_u32 v52, v52, 7, v90
	v_lshl_add_u32 v53, v53, 7, v91
	v_lshl_add_u32 v54, v54, 7, v92
	v_lshl_add_u32 v55, v55, 7, v93
	v_lshl_add_u32 v56, v56, 7, v94
	v_lshl_add_u32 v57, v57, 7, v95
	v_lshl_add_u32 v58, v58, 7, v96
	v_lshl_add_u32 v59, v59, 7, v97
	v_lshl_add_u32 v60, v60, 7, v98
	v_lshl_add_u32 v61, v61, 7, v99
	global_store_dwordx4 v[116:117], v[46:49], off
	global_store_dwordx4 v[116:117], v[50:53], off offset:16
	global_store_dwordx4 v[116:117], v[54:57], off offset:32
	global_store_dwordx4 v[116:117], v[58:61], off offset:48
	s_andn2_b64 exec, exec, s[20:21]
	s_cbranch_execnz .LBB0_1005
